# E_GU pair loop: DMA issue moved to the ds_read-free half of each stage
# speedup vs baseline: 1.1001x; 1.0018x over previous
.Lgu_pair:
	s_add_i32 s63, s63, 1
	s_mov_b32 s62, 1
	v_add_u32_e32 v109, v89, v91
	v_add_u32_e32 v114, v90, v91
	v_add_u32_e32 v115, v89, v92
	v_add_u32_e32 v119, v90, v92
	v_add_u32_e32 v121, 0x4000, v114
	v_add_u32_e32 v122, 0x4000, v119
	v_readfirstlane_b32 s50, v88
	s_mov_b64 s[72:73], 0x40000
	s_mov_b64 s[86:87], 0x4000
	s_add_u32 s51, s50, 0x4000
	s_add_u32 s52, s50, 0x8000
	s_add_u32 s53, s50, 0x2000
	s_add_u32 s54, s50, 0x6000
	s_add_u32 s55, s50, 0xa000
	s_add_u32 s56, s50, 0xc000
	s_add_u32 s57, s50, 0xe000
	s_add_u32 s58, s50, 0x12000
	v_lshl_add_u64 v[148:149], v[66:67], 0, s[72:73]
	s_mov_b32 m0, s56
	s_nop 0
	global_load_lds_dwordx4 v[148:149], off
	global_load_lds_dwordx4 v[148:149], off offset:1024
	v_lshl_add_u64 v[148:149], v[148:149], 0, s[44:45]
	s_mov_b32 m0, s57
	s_nop 0
	global_load_lds_dwordx4 v[148:149], off
	global_load_lds_dwordx4 v[148:149], off offset:1024
	v_lshl_add_u64 v[148:149], v[148:149], 0, s[44:45]
	s_mov_b32 m0, s58
	s_nop 0
	global_load_lds_dwordx4 v[148:149], off
	global_load_lds_dwordx4 v[148:149], off offset:1024
	v_lshl_add_u64 v[64:65], v[64:65], 0, s[86:87]
	v_lshl_add_u64 v[66:67], v[66:67], 0, s[86:87]
	s_waitcnt vmcnt(4)
	s_waitcnt lgkmcnt(0)
	s_barrier
	ds_read_b128 v[110:113], v109
	ds_read_b128 v[132:135], v114 offset:8192
	ds_read_b128 v[136:139], v114 offset:10240
	ds_read_b128 v[140:143], v114 offset:49152
	ds_read_b128 v[144:147], v114 offset:51200
	ds_read_b128 v[128:131], v109 offset:2048
	ds_read_b128 v[202:205], v115
	ds_read_b128 v[214:217], v119 offset:8192
	ds_read_b128 v[244:247], v119 offset:10240
	ds_read_b128 v[250:253], v119 offset:49152
	ds_read_b128 v[206:209], v115 offset:2048
	ds_read_b128 v[74:77], v119 offset:51200
	s_waitcnt lgkmcnt(6)
	v_mfma_f32_32x32x16_bf16 v[48:63], v[110:113], v[132:135], 0
	v_mfma_f32_32x32x16_bf16 v[32:47], v[110:113], v[136:139], 0
	v_mfma_f32_32x32x16_bf16 v[150:165], v[110:113], v[140:143], 0
	v_mfma_f32_32x32x16_bf16 v[166:181], v[110:113], v[144:147], 0
	v_mfma_f32_32x32x16_bf16 v[16:31], v[128:131], v[132:135], 0
	v_mfma_f32_32x32x16_bf16 v[0:15], v[128:131], v[136:139], 0
	v_mfma_f32_32x32x16_bf16 v[184:199], v[128:131], v[140:143], 0
	v_mfma_f32_32x32x16_bf16 v[226:241], v[128:131], v[144:147], 0
	s_waitcnt vmcnt(2)
	s_waitcnt lgkmcnt(0)
	s_barrier
	ds_read_b128 v[110:113], v109 offset:16384
	ds_read_b128 v[132:135], v114 offset:24576
	v_mfma_f32_32x32x16_bf16 v[48:63], v[202:205], v[214:217], v[48:63]
	ds_read_b128 v[136:139], v114 offset:26624
	ds_read_b128 v[140:143], v121 offset:40960
	v_mfma_f32_32x32x16_bf16 v[32:47], v[202:205], v[244:247], v[32:47]
	ds_read_b128 v[144:147], v121 offset:43008
	ds_read_b128 v[128:131], v109 offset:18432
	v_mfma_f32_32x32x16_bf16 v[150:165], v[202:205], v[250:253], v[150:165]
	v_mfma_f32_32x32x16_bf16 v[166:181], v[202:205], v[74:77], v[166:181]
	ds_read_b128 v[202:205], v115 offset:16384
	v_mfma_f32_32x32x16_bf16 v[16:31], v[206:209], v[214:217], v[16:31]
	ds_read_b128 v[214:217], v119 offset:24576
	v_mfma_f32_32x32x16_bf16 v[0:15], v[206:209], v[244:247], v[0:15]
	ds_read_b128 v[244:247], v119 offset:26624
	v_mfma_f32_32x32x16_bf16 v[184:199], v[206:209], v[250:253], v[184:199]
	ds_read_b128 v[250:253], v122 offset:40960
	v_mfma_f32_32x32x16_bf16 v[226:241], v[206:209], v[74:77], v[226:241]
	ds_read_b128 v[206:209], v115 offset:18432
	ds_read_b128 v[74:77], v122 offset:43008
	s_waitcnt lgkmcnt(6)
	v_mfma_f32_32x32x16_bf16 v[48:63], v[110:113], v[132:135], v[48:63]
	s_mov_b32 m0, s50
	v_lshl_add_u64 v[64:65], v[64:65], 0, s[44:45]
	global_load_lds_dwordx4 v[64:65], off
	v_mfma_f32_32x32x16_bf16 v[32:47], v[110:113], v[136:139], v[32:47]
	global_load_lds_dwordx4 v[64:65], off offset:1024
	v_mfma_f32_32x32x16_bf16 v[150:165], v[110:113], v[140:143], v[150:165]
	s_mov_b32 m0, s53
	v_lshl_add_u64 v[66:67], v[66:67], 0, s[44:45]
	global_load_lds_dwordx4 v[66:67], off
	v_mfma_f32_32x32x16_bf16 v[166:181], v[110:113], v[144:147], v[166:181]
	global_load_lds_dwordx4 v[66:67], off offset:1024
	v_mfma_f32_32x32x16_bf16 v[16:31], v[128:131], v[132:135], v[16:31]
	s_mov_b32 m0, s56
	v_lshl_add_u64 v[148:149], v[66:67], 0, s[72:73]
	global_load_lds_dwordx4 v[148:149], off
	v_mfma_f32_32x32x16_bf16 v[0:15], v[128:131], v[136:139], v[0:15]
	global_load_lds_dwordx4 v[148:149], off offset:1024
	v_mfma_f32_32x32x16_bf16 v[184:199], v[128:131], v[140:143], v[184:199]
	v_mfma_f32_32x32x16_bf16 v[226:241], v[128:131], v[144:147], v[226:241]
	s_waitcnt vmcnt(6)
	s_waitcnt lgkmcnt(0)
	s_barrier
	ds_read_b128 v[110:113], v109 offset:32768
	ds_read_b128 v[132:135], v114 offset:40960
	v_mfma_f32_32x32x16_bf16 v[48:63], v[202:205], v[214:217], v[48:63]
	ds_read_b128 v[136:139], v114 offset:43008
	ds_read_b128 v[140:143], v121 offset:57344
	v_mfma_f32_32x32x16_bf16 v[32:47], v[202:205], v[244:247], v[32:47]
	ds_read_b128 v[144:147], v121 offset:59392
	ds_read_b128 v[128:131], v109 offset:34816
	v_mfma_f32_32x32x16_bf16 v[150:165], v[202:205], v[250:253], v[150:165]
	v_mfma_f32_32x32x16_bf16 v[166:181], v[202:205], v[74:77], v[166:181]
	ds_read_b128 v[202:205], v115 offset:32768
	v_mfma_f32_32x32x16_bf16 v[16:31], v[206:209], v[214:217], v[16:31]
	ds_read_b128 v[214:217], v119 offset:40960
	v_mfma_f32_32x32x16_bf16 v[0:15], v[206:209], v[244:247], v[0:15]
	ds_read_b128 v[244:247], v119 offset:43008
	v_mfma_f32_32x32x16_bf16 v[184:199], v[206:209], v[250:253], v[184:199]
	ds_read_b128 v[250:253], v122 offset:57344
	v_mfma_f32_32x32x16_bf16 v[226:241], v[206:209], v[74:77], v[226:241]
	ds_read_b128 v[206:209], v115 offset:34816
	ds_read_b128 v[74:77], v122 offset:59392
	s_waitcnt lgkmcnt(6)
	v_mfma_f32_32x32x16_bf16 v[48:63], v[110:113], v[132:135], v[48:63]
	s_mov_b32 m0, s51
	v_lshl_add_u64 v[64:65], v[64:65], 0, s[44:45]
	global_load_lds_dwordx4 v[64:65], off
	v_mfma_f32_32x32x16_bf16 v[32:47], v[110:113], v[136:139], v[32:47]
	global_load_lds_dwordx4 v[64:65], off offset:1024
	v_mfma_f32_32x32x16_bf16 v[150:165], v[110:113], v[140:143], v[150:165]
	s_mov_b32 m0, s54
	v_lshl_add_u64 v[66:67], v[66:67], 0, s[44:45]
	global_load_lds_dwordx4 v[66:67], off
	v_mfma_f32_32x32x16_bf16 v[166:181], v[110:113], v[144:147], v[166:181]
	global_load_lds_dwordx4 v[66:67], off offset:1024
	v_mfma_f32_32x32x16_bf16 v[16:31], v[128:131], v[132:135], v[16:31]
	s_mov_b32 m0, s57
	v_lshl_add_u64 v[148:149], v[66:67], 0, s[72:73]
	global_load_lds_dwordx4 v[148:149], off
	v_mfma_f32_32x32x16_bf16 v[0:15], v[128:131], v[136:139], v[0:15]
	global_load_lds_dwordx4 v[148:149], off offset:1024
	v_mfma_f32_32x32x16_bf16 v[184:199], v[128:131], v[140:143], v[184:199]
	v_mfma_f32_32x32x16_bf16 v[226:241], v[128:131], v[144:147], v[226:241]
	s_waitcnt vmcnt(6)
	s_waitcnt lgkmcnt(0)
	s_barrier
	ds_read_b128 v[110:113], v109
	ds_read_b128 v[132:135], v114 offset:8192
	v_mfma_f32_32x32x16_bf16 v[48:63], v[202:205], v[214:217], v[48:63]
	ds_read_b128 v[136:139], v114 offset:10240
	ds_read_b128 v[140:143], v114 offset:49152
	v_mfma_f32_32x32x16_bf16 v[32:47], v[202:205], v[244:247], v[32:47]
	ds_read_b128 v[144:147], v114 offset:51200
	ds_read_b128 v[128:131], v109 offset:2048
	v_mfma_f32_32x32x16_bf16 v[150:165], v[202:205], v[250:253], v[150:165]
	v_mfma_f32_32x32x16_bf16 v[166:181], v[202:205], v[74:77], v[166:181]
	ds_read_b128 v[202:205], v115
	v_mfma_f32_32x32x16_bf16 v[16:31], v[206:209], v[214:217], v[16:31]
	ds_read_b128 v[214:217], v119 offset:8192
	v_mfma_f32_32x32x16_bf16 v[0:15], v[206:209], v[244:247], v[0:15]
	ds_read_b128 v[244:247], v119 offset:10240
	v_mfma_f32_32x32x16_bf16 v[184:199], v[206:209], v[250:253], v[184:199]
	ds_read_b128 v[250:253], v119 offset:49152
	v_mfma_f32_32x32x16_bf16 v[226:241], v[206:209], v[74:77], v[226:241]
	ds_read_b128 v[206:209], v115 offset:2048
	ds_read_b128 v[74:77], v119 offset:51200
	s_waitcnt lgkmcnt(6)
	v_mfma_f32_32x32x16_bf16 v[48:63], v[110:113], v[132:135], v[48:63]
	s_mov_b32 m0, s52
	v_lshl_add_u64 v[64:65], v[64:65], 0, s[44:45]
	global_load_lds_dwordx4 v[64:65], off
	v_mfma_f32_32x32x16_bf16 v[32:47], v[110:113], v[136:139], v[32:47]
	global_load_lds_dwordx4 v[64:65], off offset:1024
	v_mfma_f32_32x32x16_bf16 v[150:165], v[110:113], v[140:143], v[150:165]
	s_mov_b32 m0, s55
	v_lshl_add_u64 v[66:67], v[66:67], 0, s[44:45]
	global_load_lds_dwordx4 v[66:67], off
	v_mfma_f32_32x32x16_bf16 v[166:181], v[110:113], v[144:147], v[166:181]
	global_load_lds_dwordx4 v[66:67], off offset:1024
	v_mfma_f32_32x32x16_bf16 v[16:31], v[128:131], v[132:135], v[16:31]
	s_mov_b32 m0, s58
	v_lshl_add_u64 v[148:149], v[66:67], 0, s[72:73]
	global_load_lds_dwordx4 v[148:149], off
	v_mfma_f32_32x32x16_bf16 v[0:15], v[128:131], v[136:139], v[0:15]
	global_load_lds_dwordx4 v[148:149], off offset:1024
	v_mfma_f32_32x32x16_bf16 v[184:199], v[128:131], v[140:143], v[184:199]
	v_mfma_f32_32x32x16_bf16 v[226:241], v[128:131], v[144:147], v[226:241]
	s_waitcnt vmcnt(6)
	s_waitcnt lgkmcnt(0)
	s_barrier
	ds_read_b128 v[110:113], v109 offset:16384
	ds_read_b128 v[132:135], v114 offset:24576
	v_mfma_f32_32x32x16_bf16 v[48:63], v[202:205], v[214:217], v[48:63]
	ds_read_b128 v[136:139], v114 offset:26624
	ds_read_b128 v[140:143], v121 offset:40960
	v_mfma_f32_32x32x16_bf16 v[32:47], v[202:205], v[244:247], v[32:47]
	ds_read_b128 v[144:147], v121 offset:43008
	ds_read_b128 v[128:131], v109 offset:18432
	v_mfma_f32_32x32x16_bf16 v[150:165], v[202:205], v[250:253], v[150:165]
	v_mfma_f32_32x32x16_bf16 v[166:181], v[202:205], v[74:77], v[166:181]
	ds_read_b128 v[202:205], v115 offset:16384
	v_mfma_f32_32x32x16_bf16 v[16:31], v[206:209], v[214:217], v[16:31]
	ds_read_b128 v[214:217], v119 offset:24576
	v_mfma_f32_32x32x16_bf16 v[0:15], v[206:209], v[244:247], v[0:15]
	ds_read_b128 v[244:247], v119 offset:26624
	v_mfma_f32_32x32x16_bf16 v[184:199], v[206:209], v[250:253], v[184:199]
	ds_read_b128 v[250:253], v122 offset:40960
	v_mfma_f32_32x32x16_bf16 v[226:241], v[206:209], v[74:77], v[226:241]
	ds_read_b128 v[206:209], v115 offset:18432
	ds_read_b128 v[74:77], v122 offset:43008
	s_waitcnt lgkmcnt(6)
	v_mfma_f32_32x32x16_bf16 v[48:63], v[110:113], v[132:135], v[48:63]
	s_mov_b32 m0, s50
	v_lshl_add_u64 v[64:65], v[64:65], 0, s[44:45]
	global_load_lds_dwordx4 v[64:65], off
	v_mfma_f32_32x32x16_bf16 v[32:47], v[110:113], v[136:139], v[32:47]
	global_load_lds_dwordx4 v[64:65], off offset:1024
	v_mfma_f32_32x32x16_bf16 v[150:165], v[110:113], v[140:143], v[150:165]
	s_mov_b32 m0, s53
	v_lshl_add_u64 v[66:67], v[66:67], 0, s[44:45]
	global_load_lds_dwordx4 v[66:67], off
	v_mfma_f32_32x32x16_bf16 v[166:181], v[110:113], v[144:147], v[166:181]
	global_load_lds_dwordx4 v[66:67], off offset:1024
	v_mfma_f32_32x32x16_bf16 v[16:31], v[128:131], v[132:135], v[16:31]
	s_mov_b32 m0, s56
	v_lshl_add_u64 v[148:149], v[66:67], 0, s[72:73]
	global_load_lds_dwordx4 v[148:149], off
	v_mfma_f32_32x32x16_bf16 v[0:15], v[128:131], v[136:139], v[0:15]
	global_load_lds_dwordx4 v[148:149], off offset:1024
	v_mfma_f32_32x32x16_bf16 v[184:199], v[128:131], v[140:143], v[184:199]
	v_mfma_f32_32x32x16_bf16 v[226:241], v[128:131], v[144:147], v[226:241]
	s_waitcnt vmcnt(6)
	s_waitcnt lgkmcnt(0)
	s_barrier
	ds_read_b128 v[110:113], v109 offset:32768
	ds_read_b128 v[132:135], v114 offset:40960
	v_mfma_f32_32x32x16_bf16 v[48:63], v[202:205], v[214:217], v[48:63]
	ds_read_b128 v[136:139], v114 offset:43008
	ds_read_b128 v[140:143], v121 offset:57344
	v_mfma_f32_32x32x16_bf16 v[32:47], v[202:205], v[244:247], v[32:47]
	ds_read_b128 v[144:147], v121 offset:59392
	ds_read_b128 v[128:131], v109 offset:34816
	v_mfma_f32_32x32x16_bf16 v[150:165], v[202:205], v[250:253], v[150:165]
	v_mfma_f32_32x32x16_bf16 v[166:181], v[202:205], v[74:77], v[166:181]
	ds_read_b128 v[202:205], v115 offset:32768
	v_mfma_f32_32x32x16_bf16 v[16:31], v[206:209], v[214:217], v[16:31]
	ds_read_b128 v[214:217], v119 offset:40960
	v_mfma_f32_32x32x16_bf16 v[0:15], v[206:209], v[244:247], v[0:15]
	ds_read_b128 v[244:247], v119 offset:43008
	v_mfma_f32_32x32x16_bf16 v[184:199], v[206:209], v[250:253], v[184:199]
	ds_read_b128 v[250:253], v122 offset:57344
	v_mfma_f32_32x32x16_bf16 v[226:241], v[206:209], v[74:77], v[226:241]
	ds_read_b128 v[206:209], v115 offset:34816
	ds_read_b128 v[74:77], v122 offset:59392
	s_waitcnt lgkmcnt(6)
	v_mfma_f32_32x32x16_bf16 v[48:63], v[110:113], v[132:135], v[48:63]
	s_mov_b32 m0, s51
	v_lshl_add_u64 v[64:65], v[64:65], 0, s[44:45]
	global_load_lds_dwordx4 v[64:65], off
	v_mfma_f32_32x32x16_bf16 v[32:47], v[110:113], v[136:139], v[32:47]
	global_load_lds_dwordx4 v[64:65], off offset:1024
	v_mfma_f32_32x32x16_bf16 v[150:165], v[110:113], v[140:143], v[150:165]
	s_mov_b32 m0, s54
	v_lshl_add_u64 v[66:67], v[66:67], 0, s[44:45]
	global_load_lds_dwordx4 v[66:67], off
	v_mfma_f32_32x32x16_bf16 v[166:181], v[110:113], v[144:147], v[166:181]
	global_load_lds_dwordx4 v[66:67], off offset:1024
	v_mfma_f32_32x32x16_bf16 v[16:31], v[128:131], v[132:135], v[16:31]
	s_mov_b32 m0, s57
	v_lshl_add_u64 v[148:149], v[66:67], 0, s[72:73]
	global_load_lds_dwordx4 v[148:149], off
	v_mfma_f32_32x32x16_bf16 v[0:15], v[128:131], v[136:139], v[0:15]
	global_load_lds_dwordx4 v[148:149], off offset:1024
	v_mfma_f32_32x32x16_bf16 v[184:199], v[128:131], v[140:143], v[184:199]
	v_mfma_f32_32x32x16_bf16 v[226:241], v[128:131], v[144:147], v[226:241]
	s_waitcnt vmcnt(6)
	s_waitcnt lgkmcnt(0)
	s_barrier
	ds_read_b128 v[110:113], v109
	ds_read_b128 v[132:135], v114 offset:8192
	v_mfma_f32_32x32x16_bf16 v[48:63], v[202:205], v[214:217], v[48:63]
	ds_read_b128 v[136:139], v114 offset:10240
	ds_read_b128 v[140:143], v114 offset:49152
	v_mfma_f32_32x32x16_bf16 v[32:47], v[202:205], v[244:247], v[32:47]
	ds_read_b128 v[144:147], v114 offset:51200
	ds_read_b128 v[128:131], v109 offset:2048
	v_mfma_f32_32x32x16_bf16 v[150:165], v[202:205], v[250:253], v[150:165]
	v_mfma_f32_32x32x16_bf16 v[166:181], v[202:205], v[74:77], v[166:181]
	ds_read_b128 v[202:205], v115
	v_mfma_f32_32x32x16_bf16 v[16:31], v[206:209], v[214:217], v[16:31]
	ds_read_b128 v[214:217], v119 offset:8192
	v_mfma_f32_32x32x16_bf16 v[0:15], v[206:209], v[244:247], v[0:15]
	ds_read_b128 v[244:247], v119 offset:10240
	v_mfma_f32_32x32x16_bf16 v[184:199], v[206:209], v[250:253], v[184:199]
	ds_read_b128 v[250:253], v119 offset:49152
	v_mfma_f32_32x32x16_bf16 v[226:241], v[206:209], v[74:77], v[226:241]
	ds_read_b128 v[206:209], v115 offset:2048
	ds_read_b128 v[74:77], v119 offset:51200
	s_waitcnt lgkmcnt(6)
	v_mfma_f32_32x32x16_bf16 v[48:63], v[110:113], v[132:135], v[48:63]
	s_mov_b32 m0, s52
	v_lshl_add_u64 v[64:65], v[64:65], 0, s[44:45]
	global_load_lds_dwordx4 v[64:65], off
	v_mfma_f32_32x32x16_bf16 v[32:47], v[110:113], v[136:139], v[32:47]
	global_load_lds_dwordx4 v[64:65], off offset:1024
	v_mfma_f32_32x32x16_bf16 v[150:165], v[110:113], v[140:143], v[150:165]
	s_mov_b32 m0, s55
	v_lshl_add_u64 v[66:67], v[66:67], 0, s[44:45]
	global_load_lds_dwordx4 v[66:67], off
	v_mfma_f32_32x32x16_bf16 v[166:181], v[110:113], v[144:147], v[166:181]
	global_load_lds_dwordx4 v[66:67], off offset:1024
	v_mfma_f32_32x32x16_bf16 v[16:31], v[128:131], v[132:135], v[16:31]
	s_mov_b32 m0, s58
	v_lshl_add_u64 v[148:149], v[66:67], 0, s[72:73]
	global_load_lds_dwordx4 v[148:149], off
	v_mfma_f32_32x32x16_bf16 v[0:15], v[128:131], v[136:139], v[0:15]
	global_load_lds_dwordx4 v[148:149], off offset:1024
	v_mfma_f32_32x32x16_bf16 v[184:199], v[128:131], v[140:143], v[184:199]
	v_mfma_f32_32x32x16_bf16 v[226:241], v[128:131], v[144:147], v[226:241]
	s_waitcnt vmcnt(6)
	s_waitcnt lgkmcnt(0)
	s_barrier
	ds_read_b128 v[110:113], v109 offset:16384
	ds_read_b128 v[132:135], v114 offset:24576
	v_mfma_f32_32x32x16_bf16 v[48:63], v[202:205], v[214:217], v[48:63]
	ds_read_b128 v[136:139], v114 offset:26624
	ds_read_b128 v[140:143], v121 offset:40960
	v_mfma_f32_32x32x16_bf16 v[32:47], v[202:205], v[244:247], v[32:47]
	ds_read_b128 v[144:147], v121 offset:43008
	ds_read_b128 v[128:131], v109 offset:18432
	v_mfma_f32_32x32x16_bf16 v[150:165], v[202:205], v[250:253], v[150:165]
	v_mfma_f32_32x32x16_bf16 v[166:181], v[202:205], v[74:77], v[166:181]
	ds_read_b128 v[202:205], v115 offset:16384
	v_mfma_f32_32x32x16_bf16 v[16:31], v[206:209], v[214:217], v[16:31]
	ds_read_b128 v[214:217], v119 offset:24576
	v_mfma_f32_32x32x16_bf16 v[0:15], v[206:209], v[244:247], v[0:15]
	ds_read_b128 v[244:247], v119 offset:26624
	v_mfma_f32_32x32x16_bf16 v[184:199], v[206:209], v[250:253], v[184:199]
	ds_read_b128 v[250:253], v122 offset:40960
	v_mfma_f32_32x32x16_bf16 v[226:241], v[206:209], v[74:77], v[226:241]
	ds_read_b128 v[206:209], v115 offset:18432
	ds_read_b128 v[74:77], v122 offset:43008
	s_waitcnt lgkmcnt(6)
	v_mfma_f32_32x32x16_bf16 v[48:63], v[110:113], v[132:135], v[48:63]
	s_mov_b32 m0, s50
	v_lshl_add_u64 v[64:65], v[64:65], 0, s[44:45]
	global_load_lds_dwordx4 v[64:65], off
	v_mfma_f32_32x32x16_bf16 v[32:47], v[110:113], v[136:139], v[32:47]
	global_load_lds_dwordx4 v[64:65], off offset:1024
	v_mfma_f32_32x32x16_bf16 v[150:165], v[110:113], v[140:143], v[150:165]
	s_mov_b32 m0, s53
	v_lshl_add_u64 v[66:67], v[66:67], 0, s[44:45]
	global_load_lds_dwordx4 v[66:67], off
	v_mfma_f32_32x32x16_bf16 v[166:181], v[110:113], v[144:147], v[166:181]
	global_load_lds_dwordx4 v[66:67], off offset:1024
	v_mfma_f32_32x32x16_bf16 v[16:31], v[128:131], v[132:135], v[16:31]
	s_mov_b32 m0, s56
	v_lshl_add_u64 v[148:149], v[66:67], 0, s[72:73]
	global_load_lds_dwordx4 v[148:149], off
	v_mfma_f32_32x32x16_bf16 v[0:15], v[128:131], v[136:139], v[0:15]
	global_load_lds_dwordx4 v[148:149], off offset:1024
	v_mfma_f32_32x32x16_bf16 v[184:199], v[128:131], v[140:143], v[184:199]
	v_mfma_f32_32x32x16_bf16 v[226:241], v[128:131], v[144:147], v[226:241]
	s_waitcnt vmcnt(6)
	s_waitcnt lgkmcnt(0)
	s_barrier
	ds_read_b128 v[110:113], v109 offset:32768
	ds_read_b128 v[132:135], v114 offset:40960
	v_mfma_f32_32x32x16_bf16 v[48:63], v[202:205], v[214:217], v[48:63]
	ds_read_b128 v[136:139], v114 offset:43008
	ds_read_b128 v[140:143], v121 offset:57344
	v_mfma_f32_32x32x16_bf16 v[32:47], v[202:205], v[244:247], v[32:47]
	ds_read_b128 v[144:147], v121 offset:59392
	ds_read_b128 v[128:131], v109 offset:34816
	v_mfma_f32_32x32x16_bf16 v[150:165], v[202:205], v[250:253], v[150:165]
	v_mfma_f32_32x32x16_bf16 v[166:181], v[202:205], v[74:77], v[166:181]
	ds_read_b128 v[202:205], v115 offset:32768
	v_mfma_f32_32x32x16_bf16 v[16:31], v[206:209], v[214:217], v[16:31]
	ds_read_b128 v[214:217], v119 offset:40960
	v_mfma_f32_32x32x16_bf16 v[0:15], v[206:209], v[244:247], v[0:15]
	ds_read_b128 v[244:247], v119 offset:43008
	v_mfma_f32_32x32x16_bf16 v[184:199], v[206:209], v[250:253], v[184:199]
	ds_read_b128 v[250:253], v122 offset:57344
	v_mfma_f32_32x32x16_bf16 v[226:241], v[206:209], v[74:77], v[226:241]
	ds_read_b128 v[206:209], v115 offset:34816
	ds_read_b128 v[74:77], v122 offset:59392
	s_waitcnt lgkmcnt(6)
	v_mfma_f32_32x32x16_bf16 v[48:63], v[110:113], v[132:135], v[48:63]
	s_mov_b32 m0, s51
	v_lshl_add_u64 v[64:65], v[64:65], 0, s[44:45]
	global_load_lds_dwordx4 v[64:65], off
	v_mfma_f32_32x32x16_bf16 v[32:47], v[110:113], v[136:139], v[32:47]
	global_load_lds_dwordx4 v[64:65], off offset:1024
	v_mfma_f32_32x32x16_bf16 v[150:165], v[110:113], v[140:143], v[150:165]
	s_mov_b32 m0, s54
	v_lshl_add_u64 v[66:67], v[66:67], 0, s[44:45]
	global_load_lds_dwordx4 v[66:67], off
	v_mfma_f32_32x32x16_bf16 v[166:181], v[110:113], v[144:147], v[166:181]
	global_load_lds_dwordx4 v[66:67], off offset:1024
	v_mfma_f32_32x32x16_bf16 v[16:31], v[128:131], v[132:135], v[16:31]
	s_mov_b32 m0, s57
	v_lshl_add_u64 v[148:149], v[66:67], 0, s[72:73]
	global_load_lds_dwordx4 v[148:149], off
	v_mfma_f32_32x32x16_bf16 v[0:15], v[128:131], v[136:139], v[0:15]
	global_load_lds_dwordx4 v[148:149], off offset:1024
	v_mfma_f32_32x32x16_bf16 v[184:199], v[128:131], v[140:143], v[184:199]
	v_mfma_f32_32x32x16_bf16 v[226:241], v[128:131], v[144:147], v[226:241]
	s_waitcnt vmcnt(6)
	s_waitcnt lgkmcnt(0)
	s_barrier
	ds_read_b128 v[110:113], v109
	ds_read_b128 v[132:135], v114 offset:8192
	v_mfma_f32_32x32x16_bf16 v[48:63], v[202:205], v[214:217], v[48:63]
	ds_read_b128 v[136:139], v114 offset:10240
	ds_read_b128 v[140:143], v114 offset:49152
	v_mfma_f32_32x32x16_bf16 v[32:47], v[202:205], v[244:247], v[32:47]
	ds_read_b128 v[144:147], v114 offset:51200
	ds_read_b128 v[128:131], v109 offset:2048
	v_mfma_f32_32x32x16_bf16 v[150:165], v[202:205], v[250:253], v[150:165]
	v_mfma_f32_32x32x16_bf16 v[166:181], v[202:205], v[74:77], v[166:181]
	ds_read_b128 v[202:205], v115
	v_mfma_f32_32x32x16_bf16 v[16:31], v[206:209], v[214:217], v[16:31]
	ds_read_b128 v[214:217], v119 offset:8192
	v_mfma_f32_32x32x16_bf16 v[0:15], v[206:209], v[244:247], v[0:15]
	ds_read_b128 v[244:247], v119 offset:10240
	v_mfma_f32_32x32x16_bf16 v[184:199], v[206:209], v[250:253], v[184:199]
	ds_read_b128 v[250:253], v119 offset:49152
	v_mfma_f32_32x32x16_bf16 v[226:241], v[206:209], v[74:77], v[226:241]
	ds_read_b128 v[206:209], v115 offset:2048
	ds_read_b128 v[74:77], v119 offset:51200
	s_waitcnt lgkmcnt(6)
	v_mfma_f32_32x32x16_bf16 v[48:63], v[110:113], v[132:135], v[48:63]
	s_mov_b32 m0, s52
	v_lshl_add_u64 v[64:65], v[64:65], 0, s[44:45]
	global_load_lds_dwordx4 v[64:65], off
	v_mfma_f32_32x32x16_bf16 v[32:47], v[110:113], v[136:139], v[32:47]
	global_load_lds_dwordx4 v[64:65], off offset:1024
	v_mfma_f32_32x32x16_bf16 v[150:165], v[110:113], v[140:143], v[150:165]
	s_mov_b32 m0, s55
	v_lshl_add_u64 v[66:67], v[66:67], 0, s[44:45]
	global_load_lds_dwordx4 v[66:67], off
	v_mfma_f32_32x32x16_bf16 v[166:181], v[110:113], v[144:147], v[166:181]
	global_load_lds_dwordx4 v[66:67], off offset:1024
	v_mfma_f32_32x32x16_bf16 v[16:31], v[128:131], v[132:135], v[16:31]
	s_mov_b32 m0, s58
	v_lshl_add_u64 v[148:149], v[66:67], 0, s[72:73]
	global_load_lds_dwordx4 v[148:149], off
	v_mfma_f32_32x32x16_bf16 v[0:15], v[128:131], v[136:139], v[0:15]
	global_load_lds_dwordx4 v[148:149], off offset:1024
	v_mfma_f32_32x32x16_bf16 v[184:199], v[128:131], v[140:143], v[184:199]
	v_mfma_f32_32x32x16_bf16 v[226:241], v[128:131], v[144:147], v[226:241]
	s_waitcnt vmcnt(6)
	s_waitcnt lgkmcnt(0)
	s_barrier
	ds_read_b128 v[110:113], v109 offset:16384
	ds_read_b128 v[132:135], v114 offset:24576
	v_mfma_f32_32x32x16_bf16 v[48:63], v[202:205], v[214:217], v[48:63]
	ds_read_b128 v[136:139], v114 offset:26624
	ds_read_b128 v[140:143], v121 offset:40960
	v_mfma_f32_32x32x16_bf16 v[32:47], v[202:205], v[244:247], v[32:47]
	ds_read_b128 v[144:147], v121 offset:43008
	ds_read_b128 v[128:131], v109 offset:18432
	v_mfma_f32_32x32x16_bf16 v[150:165], v[202:205], v[250:253], v[150:165]
	v_mfma_f32_32x32x16_bf16 v[166:181], v[202:205], v[74:77], v[166:181]
	ds_read_b128 v[202:205], v115 offset:16384
	v_mfma_f32_32x32x16_bf16 v[16:31], v[206:209], v[214:217], v[16:31]
	ds_read_b128 v[214:217], v119 offset:24576
	v_mfma_f32_32x32x16_bf16 v[0:15], v[206:209], v[244:247], v[0:15]
	ds_read_b128 v[244:247], v119 offset:26624
	v_mfma_f32_32x32x16_bf16 v[184:199], v[206:209], v[250:253], v[184:199]
	ds_read_b128 v[250:253], v122 offset:40960
	v_mfma_f32_32x32x16_bf16 v[226:241], v[206:209], v[74:77], v[226:241]
	ds_read_b128 v[206:209], v115 offset:18432
	ds_read_b128 v[74:77], v122 offset:43008
	s_waitcnt lgkmcnt(6)
	v_mfma_f32_32x32x16_bf16 v[48:63], v[110:113], v[132:135], v[48:63]
	s_mov_b32 m0, s50
	v_lshl_add_u64 v[64:65], v[64:65], 0, s[44:45]
	global_load_lds_dwordx4 v[64:65], off
	v_mfma_f32_32x32x16_bf16 v[32:47], v[110:113], v[136:139], v[32:47]
	global_load_lds_dwordx4 v[64:65], off offset:1024
	v_mfma_f32_32x32x16_bf16 v[150:165], v[110:113], v[140:143], v[150:165]
	s_mov_b32 m0, s53
	v_lshl_add_u64 v[66:67], v[66:67], 0, s[44:45]
	global_load_lds_dwordx4 v[66:67], off
	v_mfma_f32_32x32x16_bf16 v[166:181], v[110:113], v[144:147], v[166:181]
	global_load_lds_dwordx4 v[66:67], off offset:1024
	v_mfma_f32_32x32x16_bf16 v[16:31], v[128:131], v[132:135], v[16:31]
	s_mov_b32 m0, s56
	v_lshl_add_u64 v[148:149], v[66:67], 0, s[72:73]
	global_load_lds_dwordx4 v[148:149], off
	v_mfma_f32_32x32x16_bf16 v[0:15], v[128:131], v[136:139], v[0:15]
	global_load_lds_dwordx4 v[148:149], off offset:1024
	v_mfma_f32_32x32x16_bf16 v[184:199], v[128:131], v[140:143], v[184:199]
	v_mfma_f32_32x32x16_bf16 v[226:241], v[128:131], v[144:147], v[226:241]
	s_waitcnt vmcnt(6)
	s_waitcnt lgkmcnt(0)
	s_barrier
	ds_read_b128 v[110:113], v109 offset:32768
	ds_read_b128 v[132:135], v114 offset:40960
	v_mfma_f32_32x32x16_bf16 v[48:63], v[202:205], v[214:217], v[48:63]
	ds_read_b128 v[136:139], v114 offset:43008
	ds_read_b128 v[140:143], v121 offset:57344
	v_mfma_f32_32x32x16_bf16 v[32:47], v[202:205], v[244:247], v[32:47]
	ds_read_b128 v[144:147], v121 offset:59392
	ds_read_b128 v[128:131], v109 offset:34816
	v_mfma_f32_32x32x16_bf16 v[150:165], v[202:205], v[250:253], v[150:165]
	v_mfma_f32_32x32x16_bf16 v[166:181], v[202:205], v[74:77], v[166:181]
	ds_read_b128 v[202:205], v115 offset:32768
	v_mfma_f32_32x32x16_bf16 v[16:31], v[206:209], v[214:217], v[16:31]
	ds_read_b128 v[214:217], v119 offset:40960
	v_mfma_f32_32x32x16_bf16 v[0:15], v[206:209], v[244:247], v[0:15]
	ds_read_b128 v[244:247], v119 offset:43008
	v_mfma_f32_32x32x16_bf16 v[184:199], v[206:209], v[250:253], v[184:199]
	ds_read_b128 v[250:253], v122 offset:57344
	v_mfma_f32_32x32x16_bf16 v[226:241], v[206:209], v[74:77], v[226:241]
	ds_read_b128 v[206:209], v115 offset:34816
	ds_read_b128 v[74:77], v122 offset:59392
	s_waitcnt lgkmcnt(6)
	v_mfma_f32_32x32x16_bf16 v[48:63], v[110:113], v[132:135], v[48:63]
	s_mov_b32 m0, s51
	v_lshl_add_u64 v[64:65], v[64:65], 0, s[44:45]
	global_load_lds_dwordx4 v[64:65], off
	v_mfma_f32_32x32x16_bf16 v[32:47], v[110:113], v[136:139], v[32:47]
	global_load_lds_dwordx4 v[64:65], off offset:1024
	v_mfma_f32_32x32x16_bf16 v[150:165], v[110:113], v[140:143], v[150:165]
	s_mov_b32 m0, s54
	v_lshl_add_u64 v[66:67], v[66:67], 0, s[44:45]
	global_load_lds_dwordx4 v[66:67], off
	v_mfma_f32_32x32x16_bf16 v[166:181], v[110:113], v[144:147], v[166:181]
	global_load_lds_dwordx4 v[66:67], off offset:1024
	v_mfma_f32_32x32x16_bf16 v[16:31], v[128:131], v[132:135], v[16:31]
	s_mov_b32 m0, s57
	v_lshl_add_u64 v[148:149], v[66:67], 0, s[72:73]
	global_load_lds_dwordx4 v[148:149], off
	v_mfma_f32_32x32x16_bf16 v[0:15], v[128:131], v[136:139], v[0:15]
	global_load_lds_dwordx4 v[148:149], off offset:1024
	v_mfma_f32_32x32x16_bf16 v[184:199], v[128:131], v[140:143], v[184:199]
	v_mfma_f32_32x32x16_bf16 v[226:241], v[128:131], v[144:147], v[226:241]
	s_waitcnt vmcnt(6)
	s_waitcnt lgkmcnt(0)
	s_barrier
	ds_read_b128 v[110:113], v109
	ds_read_b128 v[132:135], v114 offset:8192
	v_mfma_f32_32x32x16_bf16 v[48:63], v[202:205], v[214:217], v[48:63]
	ds_read_b128 v[136:139], v114 offset:10240
	ds_read_b128 v[140:143], v114 offset:49152
	v_mfma_f32_32x32x16_bf16 v[32:47], v[202:205], v[244:247], v[32:47]
	ds_read_b128 v[144:147], v114 offset:51200
	ds_read_b128 v[128:131], v109 offset:2048
	v_mfma_f32_32x32x16_bf16 v[150:165], v[202:205], v[250:253], v[150:165]
	v_mfma_f32_32x32x16_bf16 v[166:181], v[202:205], v[74:77], v[166:181]
	ds_read_b128 v[202:205], v115
	v_mfma_f32_32x32x16_bf16 v[16:31], v[206:209], v[214:217], v[16:31]
	ds_read_b128 v[214:217], v119 offset:8192
	v_mfma_f32_32x32x16_bf16 v[0:15], v[206:209], v[244:247], v[0:15]
	ds_read_b128 v[244:247], v119 offset:10240
	v_mfma_f32_32x32x16_bf16 v[184:199], v[206:209], v[250:253], v[184:199]
	ds_read_b128 v[250:253], v119 offset:49152
	v_mfma_f32_32x32x16_bf16 v[226:241], v[206:209], v[74:77], v[226:241]
	ds_read_b128 v[206:209], v115 offset:2048
	ds_read_b128 v[74:77], v119 offset:51200
	s_waitcnt lgkmcnt(6)
	v_mfma_f32_32x32x16_bf16 v[48:63], v[110:113], v[132:135], v[48:63]
	s_mov_b32 m0, s52
	v_lshl_add_u64 v[64:65], v[64:65], 0, s[44:45]
	global_load_lds_dwordx4 v[64:65], off
	v_mfma_f32_32x32x16_bf16 v[32:47], v[110:113], v[136:139], v[32:47]
	global_load_lds_dwordx4 v[64:65], off offset:1024
	v_mfma_f32_32x32x16_bf16 v[150:165], v[110:113], v[140:143], v[150:165]
	s_mov_b32 m0, s55
	v_lshl_add_u64 v[66:67], v[66:67], 0, s[44:45]
	global_load_lds_dwordx4 v[66:67], off
	v_mfma_f32_32x32x16_bf16 v[166:181], v[110:113], v[144:147], v[166:181]
	global_load_lds_dwordx4 v[66:67], off offset:1024
	v_mfma_f32_32x32x16_bf16 v[16:31], v[128:131], v[132:135], v[16:31]
	s_mov_b32 m0, s58
	v_lshl_add_u64 v[148:149], v[66:67], 0, s[72:73]
	global_load_lds_dwordx4 v[148:149], off
	v_mfma_f32_32x32x16_bf16 v[0:15], v[128:131], v[136:139], v[0:15]
	global_load_lds_dwordx4 v[148:149], off offset:1024
	v_mfma_f32_32x32x16_bf16 v[184:199], v[128:131], v[140:143], v[184:199]
	v_mfma_f32_32x32x16_bf16 v[226:241], v[128:131], v[144:147], v[226:241]
	s_waitcnt vmcnt(6)
	s_waitcnt lgkmcnt(0)
	s_barrier
	ds_read_b128 v[110:113], v109 offset:16384
	ds_read_b128 v[132:135], v114 offset:24576
	v_mfma_f32_32x32x16_bf16 v[48:63], v[202:205], v[214:217], v[48:63]
	ds_read_b128 v[136:139], v114 offset:26624
	ds_read_b128 v[140:143], v121 offset:40960
	v_mfma_f32_32x32x16_bf16 v[32:47], v[202:205], v[244:247], v[32:47]
	ds_read_b128 v[144:147], v121 offset:43008
	ds_read_b128 v[128:131], v109 offset:18432
	v_mfma_f32_32x32x16_bf16 v[150:165], v[202:205], v[250:253], v[150:165]
	v_mfma_f32_32x32x16_bf16 v[166:181], v[202:205], v[74:77], v[166:181]
	ds_read_b128 v[202:205], v115 offset:16384
	v_mfma_f32_32x32x16_bf16 v[16:31], v[206:209], v[214:217], v[16:31]
	ds_read_b128 v[214:217], v119 offset:24576
	v_mfma_f32_32x32x16_bf16 v[0:15], v[206:209], v[244:247], v[0:15]
	ds_read_b128 v[244:247], v119 offset:26624
	v_mfma_f32_32x32x16_bf16 v[184:199], v[206:209], v[250:253], v[184:199]
	ds_read_b128 v[250:253], v122 offset:40960
	v_mfma_f32_32x32x16_bf16 v[226:241], v[206:209], v[74:77], v[226:241]
	ds_read_b128 v[206:209], v115 offset:18432
	ds_read_b128 v[74:77], v122 offset:43008
	s_waitcnt lgkmcnt(6)
	v_mfma_f32_32x32x16_bf16 v[48:63], v[110:113], v[132:135], v[48:63]
	s_mov_b32 m0, s50
	v_lshl_add_u64 v[64:65], v[64:65], 0, s[44:45]
	global_load_lds_dwordx4 v[64:65], off
	v_mfma_f32_32x32x16_bf16 v[32:47], v[110:113], v[136:139], v[32:47]
	global_load_lds_dwordx4 v[64:65], off offset:1024
	v_mfma_f32_32x32x16_bf16 v[150:165], v[110:113], v[140:143], v[150:165]
	s_mov_b32 m0, s53
	v_lshl_add_u64 v[66:67], v[66:67], 0, s[44:45]
	global_load_lds_dwordx4 v[66:67], off
	v_mfma_f32_32x32x16_bf16 v[166:181], v[110:113], v[144:147], v[166:181]
	global_load_lds_dwordx4 v[66:67], off offset:1024
	v_mfma_f32_32x32x16_bf16 v[16:31], v[128:131], v[132:135], v[16:31]
	s_mov_b32 m0, s56
	v_lshl_add_u64 v[148:149], v[66:67], 0, s[72:73]
	global_load_lds_dwordx4 v[148:149], off
	v_mfma_f32_32x32x16_bf16 v[0:15], v[128:131], v[136:139], v[0:15]
	global_load_lds_dwordx4 v[148:149], off offset:1024
	v_mfma_f32_32x32x16_bf16 v[184:199], v[128:131], v[140:143], v[184:199]
	v_mfma_f32_32x32x16_bf16 v[226:241], v[128:131], v[144:147], v[226:241]
	s_waitcnt vmcnt(6)
	s_waitcnt lgkmcnt(0)
	s_barrier
	ds_read_b128 v[110:113], v109 offset:32768
	ds_read_b128 v[132:135], v114 offset:40960
	v_mfma_f32_32x32x16_bf16 v[48:63], v[202:205], v[214:217], v[48:63]
	ds_read_b128 v[136:139], v114 offset:43008
	ds_read_b128 v[140:143], v121 offset:57344
	v_mfma_f32_32x32x16_bf16 v[32:47], v[202:205], v[244:247], v[32:47]
	ds_read_b128 v[144:147], v121 offset:59392
	ds_read_b128 v[128:131], v109 offset:34816
	v_mfma_f32_32x32x16_bf16 v[150:165], v[202:205], v[250:253], v[150:165]
	v_mfma_f32_32x32x16_bf16 v[166:181], v[202:205], v[74:77], v[166:181]
	ds_read_b128 v[202:205], v115 offset:32768
	v_mfma_f32_32x32x16_bf16 v[16:31], v[206:209], v[214:217], v[16:31]
	ds_read_b128 v[214:217], v119 offset:40960
	v_mfma_f32_32x32x16_bf16 v[0:15], v[206:209], v[244:247], v[0:15]
	ds_read_b128 v[244:247], v119 offset:43008
	v_mfma_f32_32x32x16_bf16 v[184:199], v[206:209], v[250:253], v[184:199]
	ds_read_b128 v[250:253], v122 offset:57344
	v_mfma_f32_32x32x16_bf16 v[226:241], v[206:209], v[74:77], v[226:241]
	ds_read_b128 v[206:209], v115 offset:34816
	ds_read_b128 v[74:77], v122 offset:59392
	s_waitcnt lgkmcnt(6)
	v_mfma_f32_32x32x16_bf16 v[48:63], v[110:113], v[132:135], v[48:63]
	s_mov_b32 m0, s51
	v_lshl_add_u64 v[64:65], v[64:65], 0, s[44:45]
	global_load_lds_dwordx4 v[64:65], off
	v_mfma_f32_32x32x16_bf16 v[32:47], v[110:113], v[136:139], v[32:47]
	global_load_lds_dwordx4 v[64:65], off offset:1024
	v_mfma_f32_32x32x16_bf16 v[150:165], v[110:113], v[140:143], v[150:165]
	s_mov_b32 m0, s54
	v_lshl_add_u64 v[66:67], v[66:67], 0, s[44:45]
	global_load_lds_dwordx4 v[66:67], off
	v_mfma_f32_32x32x16_bf16 v[166:181], v[110:113], v[144:147], v[166:181]
	global_load_lds_dwordx4 v[66:67], off offset:1024
	v_mfma_f32_32x32x16_bf16 v[16:31], v[128:131], v[132:135], v[16:31]
	s_mov_b32 m0, s57
	v_lshl_add_u64 v[148:149], v[66:67], 0, s[72:73]
	global_load_lds_dwordx4 v[148:149], off
	v_mfma_f32_32x32x16_bf16 v[0:15], v[128:131], v[136:139], v[0:15]
	global_load_lds_dwordx4 v[148:149], off offset:1024
	v_mfma_f32_32x32x16_bf16 v[184:199], v[128:131], v[140:143], v[184:199]
	v_mfma_f32_32x32x16_bf16 v[226:241], v[128:131], v[144:147], v[226:241]
	s_waitcnt vmcnt(6)
	s_waitcnt lgkmcnt(0)
	s_barrier
	ds_read_b128 v[110:113], v109
	ds_read_b128 v[132:135], v114 offset:8192
	v_mfma_f32_32x32x16_bf16 v[48:63], v[202:205], v[214:217], v[48:63]
	ds_read_b128 v[136:139], v114 offset:10240
	ds_read_b128 v[140:143], v114 offset:49152
	v_mfma_f32_32x32x16_bf16 v[32:47], v[202:205], v[244:247], v[32:47]
	ds_read_b128 v[144:147], v114 offset:51200
	ds_read_b128 v[128:131], v109 offset:2048
	v_mfma_f32_32x32x16_bf16 v[150:165], v[202:205], v[250:253], v[150:165]
	v_mfma_f32_32x32x16_bf16 v[166:181], v[202:205], v[74:77], v[166:181]
	ds_read_b128 v[202:205], v115
	v_mfma_f32_32x32x16_bf16 v[16:31], v[206:209], v[214:217], v[16:31]
	ds_read_b128 v[214:217], v119 offset:8192
	v_mfma_f32_32x32x16_bf16 v[0:15], v[206:209], v[244:247], v[0:15]
	ds_read_b128 v[244:247], v119 offset:10240
	v_mfma_f32_32x32x16_bf16 v[184:199], v[206:209], v[250:253], v[184:199]
	ds_read_b128 v[250:253], v119 offset:49152
	v_mfma_f32_32x32x16_bf16 v[226:241], v[206:209], v[74:77], v[226:241]
	ds_read_b128 v[206:209], v115 offset:2048
	ds_read_b128 v[74:77], v119 offset:51200
	s_waitcnt lgkmcnt(6)
	v_mfma_f32_32x32x16_bf16 v[48:63], v[110:113], v[132:135], v[48:63]
	s_mov_b32 m0, s52
	v_lshl_add_u64 v[64:65], v[64:65], 0, s[44:45]
	global_load_lds_dwordx4 v[64:65], off
	v_mfma_f32_32x32x16_bf16 v[32:47], v[110:113], v[136:139], v[32:47]
	global_load_lds_dwordx4 v[64:65], off offset:1024
	v_mfma_f32_32x32x16_bf16 v[150:165], v[110:113], v[140:143], v[150:165]
	s_mov_b32 m0, s55
	v_lshl_add_u64 v[66:67], v[66:67], 0, s[44:45]
	global_load_lds_dwordx4 v[66:67], off
	v_mfma_f32_32x32x16_bf16 v[166:181], v[110:113], v[144:147], v[166:181]
	global_load_lds_dwordx4 v[66:67], off offset:1024
	v_mfma_f32_32x32x16_bf16 v[16:31], v[128:131], v[132:135], v[16:31]
	s_mov_b32 m0, s58
	v_lshl_add_u64 v[148:149], v[66:67], 0, s[72:73]
	global_load_lds_dwordx4 v[148:149], off
	v_mfma_f32_32x32x16_bf16 v[0:15], v[128:131], v[136:139], v[0:15]
	global_load_lds_dwordx4 v[148:149], off offset:1024
	v_mfma_f32_32x32x16_bf16 v[184:199], v[128:131], v[140:143], v[184:199]
	v_mfma_f32_32x32x16_bf16 v[226:241], v[128:131], v[144:147], v[226:241]
	s_waitcnt vmcnt(6)
	s_waitcnt lgkmcnt(0)
	s_barrier
	ds_read_b128 v[110:113], v109 offset:16384
	ds_read_b128 v[132:135], v114 offset:24576
	v_mfma_f32_32x32x16_bf16 v[48:63], v[202:205], v[214:217], v[48:63]
	ds_read_b128 v[136:139], v114 offset:26624
	ds_read_b128 v[140:143], v121 offset:40960
	v_mfma_f32_32x32x16_bf16 v[32:47], v[202:205], v[244:247], v[32:47]
	ds_read_b128 v[144:147], v121 offset:43008
	ds_read_b128 v[128:131], v109 offset:18432
	v_mfma_f32_32x32x16_bf16 v[150:165], v[202:205], v[250:253], v[150:165]
	v_mfma_f32_32x32x16_bf16 v[166:181], v[202:205], v[74:77], v[166:181]
	ds_read_b128 v[202:205], v115 offset:16384
	v_mfma_f32_32x32x16_bf16 v[16:31], v[206:209], v[214:217], v[16:31]
	ds_read_b128 v[214:217], v119 offset:24576
	v_mfma_f32_32x32x16_bf16 v[0:15], v[206:209], v[244:247], v[0:15]
	ds_read_b128 v[244:247], v119 offset:26624
	v_mfma_f32_32x32x16_bf16 v[184:199], v[206:209], v[250:253], v[184:199]
	ds_read_b128 v[250:253], v122 offset:40960
	v_mfma_f32_32x32x16_bf16 v[226:241], v[206:209], v[74:77], v[226:241]
	ds_read_b128 v[206:209], v115 offset:18432
	ds_read_b128 v[74:77], v122 offset:43008
	s_waitcnt lgkmcnt(6)
	v_mfma_f32_32x32x16_bf16 v[48:63], v[110:113], v[132:135], v[48:63]
	s_mov_b32 m0, s50
	v_lshl_add_u64 v[64:65], v[64:65], 0, s[44:45]
	global_load_lds_dwordx4 v[64:65], off
	v_mfma_f32_32x32x16_bf16 v[32:47], v[110:113], v[136:139], v[32:47]
	global_load_lds_dwordx4 v[64:65], off offset:1024
	v_mfma_f32_32x32x16_bf16 v[150:165], v[110:113], v[140:143], v[150:165]
	s_mov_b32 m0, s53
	v_lshl_add_u64 v[66:67], v[66:67], 0, s[44:45]
	global_load_lds_dwordx4 v[66:67], off
	v_mfma_f32_32x32x16_bf16 v[166:181], v[110:113], v[144:147], v[166:181]
	global_load_lds_dwordx4 v[66:67], off offset:1024
	v_mfma_f32_32x32x16_bf16 v[16:31], v[128:131], v[132:135], v[16:31]
	s_mov_b32 m0, s56
	v_lshl_add_u64 v[148:149], v[66:67], 0, s[72:73]
	global_load_lds_dwordx4 v[148:149], off
	v_mfma_f32_32x32x16_bf16 v[0:15], v[128:131], v[136:139], v[0:15]
	global_load_lds_dwordx4 v[148:149], off offset:1024
	v_mfma_f32_32x32x16_bf16 v[184:199], v[128:131], v[140:143], v[184:199]
	v_mfma_f32_32x32x16_bf16 v[226:241], v[128:131], v[144:147], v[226:241]
	s_waitcnt vmcnt(6)
	s_waitcnt lgkmcnt(0)
	s_barrier
	ds_read_b128 v[110:113], v109 offset:32768
	ds_read_b128 v[132:135], v114 offset:40960
	v_mfma_f32_32x32x16_bf16 v[48:63], v[202:205], v[214:217], v[48:63]
	ds_read_b128 v[136:139], v114 offset:43008
	ds_read_b128 v[140:143], v121 offset:57344
	v_mfma_f32_32x32x16_bf16 v[32:47], v[202:205], v[244:247], v[32:47]
	ds_read_b128 v[144:147], v121 offset:59392
	ds_read_b128 v[128:131], v109 offset:34816
	v_mfma_f32_32x32x16_bf16 v[150:165], v[202:205], v[250:253], v[150:165]
	v_mfma_f32_32x32x16_bf16 v[166:181], v[202:205], v[74:77], v[166:181]
	ds_read_b128 v[202:205], v115 offset:32768
	v_mfma_f32_32x32x16_bf16 v[16:31], v[206:209], v[214:217], v[16:31]
	ds_read_b128 v[214:217], v119 offset:40960
	v_mfma_f32_32x32x16_bf16 v[0:15], v[206:209], v[244:247], v[0:15]
	ds_read_b128 v[244:247], v119 offset:43008
	v_mfma_f32_32x32x16_bf16 v[184:199], v[206:209], v[250:253], v[184:199]
	ds_read_b128 v[250:253], v122 offset:57344
	v_mfma_f32_32x32x16_bf16 v[226:241], v[206:209], v[74:77], v[226:241]
	ds_read_b128 v[206:209], v115 offset:34816
	ds_read_b128 v[74:77], v122 offset:59392
	s_waitcnt lgkmcnt(6)
	v_mfma_f32_32x32x16_bf16 v[48:63], v[110:113], v[132:135], v[48:63]
	s_mov_b32 m0, s51
	v_lshl_add_u64 v[64:65], v[64:65], 0, s[44:45]
	global_load_lds_dwordx4 v[64:65], off
	v_mfma_f32_32x32x16_bf16 v[32:47], v[110:113], v[136:139], v[32:47]
	global_load_lds_dwordx4 v[64:65], off offset:1024
	v_mfma_f32_32x32x16_bf16 v[150:165], v[110:113], v[140:143], v[150:165]
	s_mov_b32 m0, s54
	v_lshl_add_u64 v[66:67], v[66:67], 0, s[44:45]
	global_load_lds_dwordx4 v[66:67], off
	v_mfma_f32_32x32x16_bf16 v[166:181], v[110:113], v[144:147], v[166:181]
	global_load_lds_dwordx4 v[66:67], off offset:1024
	v_mfma_f32_32x32x16_bf16 v[16:31], v[128:131], v[132:135], v[16:31]
	s_mov_b32 m0, s57
	v_lshl_add_u64 v[148:149], v[66:67], 0, s[72:73]
	global_load_lds_dwordx4 v[148:149], off
	v_mfma_f32_32x32x16_bf16 v[0:15], v[128:131], v[136:139], v[0:15]
	global_load_lds_dwordx4 v[148:149], off offset:1024
	v_mfma_f32_32x32x16_bf16 v[184:199], v[128:131], v[140:143], v[184:199]
	v_mfma_f32_32x32x16_bf16 v[226:241], v[128:131], v[144:147], v[226:241]
	s_waitcnt vmcnt(6)
	s_waitcnt lgkmcnt(0)
	s_barrier
	ds_read_b128 v[110:113], v109
	ds_read_b128 v[132:135], v114 offset:8192
	v_mfma_f32_32x32x16_bf16 v[48:63], v[202:205], v[214:217], v[48:63]
	ds_read_b128 v[136:139], v114 offset:10240
	ds_read_b128 v[140:143], v114 offset:49152
	v_mfma_f32_32x32x16_bf16 v[32:47], v[202:205], v[244:247], v[32:47]
	ds_read_b128 v[144:147], v114 offset:51200
	ds_read_b128 v[128:131], v109 offset:2048
	v_mfma_f32_32x32x16_bf16 v[150:165], v[202:205], v[250:253], v[150:165]
	v_mfma_f32_32x32x16_bf16 v[166:181], v[202:205], v[74:77], v[166:181]
	ds_read_b128 v[202:205], v115
	v_mfma_f32_32x32x16_bf16 v[16:31], v[206:209], v[214:217], v[16:31]
	ds_read_b128 v[214:217], v119 offset:8192
	v_mfma_f32_32x32x16_bf16 v[0:15], v[206:209], v[244:247], v[0:15]
	ds_read_b128 v[244:247], v119 offset:10240
	v_mfma_f32_32x32x16_bf16 v[184:199], v[206:209], v[250:253], v[184:199]
	ds_read_b128 v[250:253], v119 offset:49152
	v_mfma_f32_32x32x16_bf16 v[226:241], v[206:209], v[74:77], v[226:241]
	ds_read_b128 v[206:209], v115 offset:2048
	ds_read_b128 v[74:77], v119 offset:51200
	s_waitcnt lgkmcnt(6)
	v_mfma_f32_32x32x16_bf16 v[48:63], v[110:113], v[132:135], v[48:63]
	s_mov_b32 m0, s52
	v_lshl_add_u64 v[64:65], v[64:65], 0, s[44:45]
	global_load_lds_dwordx4 v[64:65], off
	v_mfma_f32_32x32x16_bf16 v[32:47], v[110:113], v[136:139], v[32:47]
	global_load_lds_dwordx4 v[64:65], off offset:1024
	v_mfma_f32_32x32x16_bf16 v[150:165], v[110:113], v[140:143], v[150:165]
	s_mov_b32 m0, s55
	v_lshl_add_u64 v[66:67], v[66:67], 0, s[44:45]
	global_load_lds_dwordx4 v[66:67], off
	v_mfma_f32_32x32x16_bf16 v[166:181], v[110:113], v[144:147], v[166:181]
	global_load_lds_dwordx4 v[66:67], off offset:1024
	v_mfma_f32_32x32x16_bf16 v[16:31], v[128:131], v[132:135], v[16:31]
	s_mov_b32 m0, s58
	v_lshl_add_u64 v[148:149], v[66:67], 0, s[72:73]
	global_load_lds_dwordx4 v[148:149], off
	v_mfma_f32_32x32x16_bf16 v[0:15], v[128:131], v[136:139], v[0:15]
	global_load_lds_dwordx4 v[148:149], off offset:1024
	v_mfma_f32_32x32x16_bf16 v[184:199], v[128:131], v[140:143], v[184:199]
	v_mfma_f32_32x32x16_bf16 v[226:241], v[128:131], v[144:147], v[226:241]
	s_waitcnt vmcnt(6)
	s_waitcnt lgkmcnt(0)
	s_barrier
	ds_read_b128 v[110:113], v109 offset:16384
	ds_read_b128 v[132:135], v114 offset:24576
	v_mfma_f32_32x32x16_bf16 v[48:63], v[202:205], v[214:217], v[48:63]
	ds_read_b128 v[136:139], v114 offset:26624
	ds_read_b128 v[140:143], v121 offset:40960
	v_mfma_f32_32x32x16_bf16 v[32:47], v[202:205], v[244:247], v[32:47]
	ds_read_b128 v[144:147], v121 offset:43008
	ds_read_b128 v[128:131], v109 offset:18432
	v_mfma_f32_32x32x16_bf16 v[150:165], v[202:205], v[250:253], v[150:165]
	v_mfma_f32_32x32x16_bf16 v[166:181], v[202:205], v[74:77], v[166:181]
	ds_read_b128 v[202:205], v115 offset:16384
	v_mfma_f32_32x32x16_bf16 v[16:31], v[206:209], v[214:217], v[16:31]
	ds_read_b128 v[214:217], v119 offset:24576
	v_mfma_f32_32x32x16_bf16 v[0:15], v[206:209], v[244:247], v[0:15]
	ds_read_b128 v[244:247], v119 offset:26624
	v_mfma_f32_32x32x16_bf16 v[184:199], v[206:209], v[250:253], v[184:199]
	ds_read_b128 v[250:253], v122 offset:40960
	v_mfma_f32_32x32x16_bf16 v[226:241], v[206:209], v[74:77], v[226:241]
	ds_read_b128 v[206:209], v115 offset:18432
	ds_read_b128 v[74:77], v122 offset:43008
	s_waitcnt lgkmcnt(6)
	v_mfma_f32_32x32x16_bf16 v[48:63], v[110:113], v[132:135], v[48:63]
	s_mov_b32 m0, s50
	v_lshl_add_u64 v[64:65], v[64:65], 0, s[44:45]
	global_load_lds_dwordx4 v[64:65], off
	v_mfma_f32_32x32x16_bf16 v[32:47], v[110:113], v[136:139], v[32:47]
	global_load_lds_dwordx4 v[64:65], off offset:1024
	v_mfma_f32_32x32x16_bf16 v[150:165], v[110:113], v[140:143], v[150:165]
	s_mov_b32 m0, s53
	v_lshl_add_u64 v[66:67], v[66:67], 0, s[44:45]
	global_load_lds_dwordx4 v[66:67], off
	v_mfma_f32_32x32x16_bf16 v[166:181], v[110:113], v[144:147], v[166:181]
	global_load_lds_dwordx4 v[66:67], off offset:1024
	v_mfma_f32_32x32x16_bf16 v[16:31], v[128:131], v[132:135], v[16:31]
	s_mov_b32 m0, s56
	v_lshl_add_u64 v[148:149], v[66:67], 0, s[72:73]
	global_load_lds_dwordx4 v[148:149], off
	v_mfma_f32_32x32x16_bf16 v[0:15], v[128:131], v[136:139], v[0:15]
	global_load_lds_dwordx4 v[148:149], off offset:1024
	v_mfma_f32_32x32x16_bf16 v[184:199], v[128:131], v[140:143], v[184:199]
	v_mfma_f32_32x32x16_bf16 v[226:241], v[128:131], v[144:147], v[226:241]
	s_waitcnt vmcnt(6)
	s_waitcnt lgkmcnt(0)
	s_barrier
	ds_read_b128 v[110:113], v109 offset:32768
	ds_read_b128 v[132:135], v114 offset:40960
	v_mfma_f32_32x32x16_bf16 v[48:63], v[202:205], v[214:217], v[48:63]
	ds_read_b128 v[136:139], v114 offset:43008
	ds_read_b128 v[140:143], v121 offset:57344
	v_mfma_f32_32x32x16_bf16 v[32:47], v[202:205], v[244:247], v[32:47]
	ds_read_b128 v[144:147], v121 offset:59392
	ds_read_b128 v[128:131], v109 offset:34816
	v_mfma_f32_32x32x16_bf16 v[150:165], v[202:205], v[250:253], v[150:165]
	v_mfma_f32_32x32x16_bf16 v[166:181], v[202:205], v[74:77], v[166:181]
	ds_read_b128 v[202:205], v115 offset:32768
	v_mfma_f32_32x32x16_bf16 v[16:31], v[206:209], v[214:217], v[16:31]
	ds_read_b128 v[214:217], v119 offset:40960
	v_mfma_f32_32x32x16_bf16 v[0:15], v[206:209], v[244:247], v[0:15]
	ds_read_b128 v[244:247], v119 offset:43008
	v_mfma_f32_32x32x16_bf16 v[184:199], v[206:209], v[250:253], v[184:199]
	ds_read_b128 v[250:253], v122 offset:57344
	v_mfma_f32_32x32x16_bf16 v[226:241], v[206:209], v[74:77], v[226:241]
	ds_read_b128 v[206:209], v115 offset:34816
	ds_read_b128 v[74:77], v122 offset:59392
	s_waitcnt lgkmcnt(6)
	v_mfma_f32_32x32x16_bf16 v[48:63], v[110:113], v[132:135], v[48:63]
	s_mov_b32 m0, s51
	v_lshl_add_u64 v[64:65], v[64:65], 0, s[44:45]
	global_load_lds_dwordx4 v[64:65], off
	v_mfma_f32_32x32x16_bf16 v[32:47], v[110:113], v[136:139], v[32:47]
	global_load_lds_dwordx4 v[64:65], off offset:1024
	v_mfma_f32_32x32x16_bf16 v[150:165], v[110:113], v[140:143], v[150:165]
	s_mov_b32 m0, s54
	v_lshl_add_u64 v[66:67], v[66:67], 0, s[44:45]
	global_load_lds_dwordx4 v[66:67], off
	v_mfma_f32_32x32x16_bf16 v[166:181], v[110:113], v[144:147], v[166:181]
	global_load_lds_dwordx4 v[66:67], off offset:1024
	v_mfma_f32_32x32x16_bf16 v[16:31], v[128:131], v[132:135], v[16:31]
	s_mov_b32 m0, s57
	v_lshl_add_u64 v[148:149], v[66:67], 0, s[72:73]
	global_load_lds_dwordx4 v[148:149], off
	v_mfma_f32_32x32x16_bf16 v[0:15], v[128:131], v[136:139], v[0:15]
	global_load_lds_dwordx4 v[148:149], off offset:1024
	v_mfma_f32_32x32x16_bf16 v[184:199], v[128:131], v[140:143], v[184:199]
	v_mfma_f32_32x32x16_bf16 v[226:241], v[128:131], v[144:147], v[226:241]
	s_waitcnt vmcnt(6)
	s_waitcnt lgkmcnt(0)
	s_barrier
	ds_read_b128 v[110:113], v109
	ds_read_b128 v[132:135], v114 offset:8192
	v_mfma_f32_32x32x16_bf16 v[48:63], v[202:205], v[214:217], v[48:63]
	ds_read_b128 v[136:139], v114 offset:10240
	ds_read_b128 v[140:143], v114 offset:49152
	v_mfma_f32_32x32x16_bf16 v[32:47], v[202:205], v[244:247], v[32:47]
	ds_read_b128 v[144:147], v114 offset:51200
	ds_read_b128 v[128:131], v109 offset:2048
	v_mfma_f32_32x32x16_bf16 v[150:165], v[202:205], v[250:253], v[150:165]
	v_mfma_f32_32x32x16_bf16 v[166:181], v[202:205], v[74:77], v[166:181]
	ds_read_b128 v[202:205], v115
	v_mfma_f32_32x32x16_bf16 v[16:31], v[206:209], v[214:217], v[16:31]
	ds_read_b128 v[214:217], v119 offset:8192
	v_mfma_f32_32x32x16_bf16 v[0:15], v[206:209], v[244:247], v[0:15]
	ds_read_b128 v[244:247], v119 offset:10240
	v_mfma_f32_32x32x16_bf16 v[184:199], v[206:209], v[250:253], v[184:199]
	ds_read_b128 v[250:253], v119 offset:49152
	v_mfma_f32_32x32x16_bf16 v[226:241], v[206:209], v[74:77], v[226:241]
	ds_read_b128 v[206:209], v115 offset:2048
	ds_read_b128 v[74:77], v119 offset:51200
	s_waitcnt lgkmcnt(6)
	v_mfma_f32_32x32x16_bf16 v[48:63], v[110:113], v[132:135], v[48:63]
	s_mov_b32 m0, s52
	v_lshl_add_u64 v[64:65], v[64:65], 0, s[44:45]
	global_load_lds_dwordx4 v[64:65], off
	v_mfma_f32_32x32x16_bf16 v[32:47], v[110:113], v[136:139], v[32:47]
	global_load_lds_dwordx4 v[64:65], off offset:1024
	v_mfma_f32_32x32x16_bf16 v[150:165], v[110:113], v[140:143], v[150:165]
	s_mov_b32 m0, s55
	v_lshl_add_u64 v[66:67], v[66:67], 0, s[44:45]
	global_load_lds_dwordx4 v[66:67], off
	v_mfma_f32_32x32x16_bf16 v[166:181], v[110:113], v[144:147], v[166:181]
	global_load_lds_dwordx4 v[66:67], off offset:1024
	v_mfma_f32_32x32x16_bf16 v[16:31], v[128:131], v[132:135], v[16:31]
	s_mov_b32 m0, s58
	v_lshl_add_u64 v[148:149], v[66:67], 0, s[72:73]
	global_load_lds_dwordx4 v[148:149], off
	v_mfma_f32_32x32x16_bf16 v[0:15], v[128:131], v[136:139], v[0:15]
	global_load_lds_dwordx4 v[148:149], off offset:1024
	v_mfma_f32_32x32x16_bf16 v[184:199], v[128:131], v[140:143], v[184:199]
	v_mfma_f32_32x32x16_bf16 v[226:241], v[128:131], v[144:147], v[226:241]
	s_waitcnt vmcnt(6)
	s_waitcnt lgkmcnt(0)
	s_barrier
	ds_read_b128 v[110:113], v109 offset:16384
	ds_read_b128 v[132:135], v114 offset:24576
	v_mfma_f32_32x32x16_bf16 v[48:63], v[202:205], v[214:217], v[48:63]
	ds_read_b128 v[136:139], v114 offset:26624
	ds_read_b128 v[140:143], v121 offset:40960
	v_mfma_f32_32x32x16_bf16 v[32:47], v[202:205], v[244:247], v[32:47]
	ds_read_b128 v[144:147], v121 offset:43008
	ds_read_b128 v[128:131], v109 offset:18432
	v_mfma_f32_32x32x16_bf16 v[150:165], v[202:205], v[250:253], v[150:165]
	v_mfma_f32_32x32x16_bf16 v[166:181], v[202:205], v[74:77], v[166:181]
	ds_read_b128 v[202:205], v115 offset:16384
	v_mfma_f32_32x32x16_bf16 v[16:31], v[206:209], v[214:217], v[16:31]
	ds_read_b128 v[214:217], v119 offset:24576
	v_mfma_f32_32x32x16_bf16 v[0:15], v[206:209], v[244:247], v[0:15]
	ds_read_b128 v[244:247], v119 offset:26624
	v_mfma_f32_32x32x16_bf16 v[184:199], v[206:209], v[250:253], v[184:199]
	ds_read_b128 v[250:253], v122 offset:40960
	v_mfma_f32_32x32x16_bf16 v[226:241], v[206:209], v[74:77], v[226:241]
	ds_read_b128 v[206:209], v115 offset:18432
	ds_read_b128 v[74:77], v122 offset:43008
	s_waitcnt lgkmcnt(6)
	v_mfma_f32_32x32x16_bf16 v[48:63], v[110:113], v[132:135], v[48:63]
	s_mov_b32 m0, s50
	v_lshl_add_u64 v[64:65], v[64:65], 0, s[44:45]
	global_load_lds_dwordx4 v[64:65], off
	v_mfma_f32_32x32x16_bf16 v[32:47], v[110:113], v[136:139], v[32:47]
	global_load_lds_dwordx4 v[64:65], off offset:1024
	v_mfma_f32_32x32x16_bf16 v[150:165], v[110:113], v[140:143], v[150:165]
	s_mov_b32 m0, s53
	v_lshl_add_u64 v[66:67], v[66:67], 0, s[44:45]
	global_load_lds_dwordx4 v[66:67], off
	v_mfma_f32_32x32x16_bf16 v[166:181], v[110:113], v[144:147], v[166:181]
	global_load_lds_dwordx4 v[66:67], off offset:1024
	v_mfma_f32_32x32x16_bf16 v[16:31], v[128:131], v[132:135], v[16:31]
	s_mov_b32 m0, s56
	v_lshl_add_u64 v[148:149], v[66:67], 0, s[72:73]
	global_load_lds_dwordx4 v[148:149], off
	v_mfma_f32_32x32x16_bf16 v[0:15], v[128:131], v[136:139], v[0:15]
	global_load_lds_dwordx4 v[148:149], off offset:1024
	v_mfma_f32_32x32x16_bf16 v[184:199], v[128:131], v[140:143], v[184:199]
	v_mfma_f32_32x32x16_bf16 v[226:241], v[128:131], v[144:147], v[226:241]
	s_waitcnt vmcnt(6)
	s_waitcnt lgkmcnt(0)
	s_barrier
	ds_read_b128 v[110:113], v109 offset:32768
	ds_read_b128 v[132:135], v114 offset:40960
	v_mfma_f32_32x32x16_bf16 v[48:63], v[202:205], v[214:217], v[48:63]
	ds_read_b128 v[136:139], v114 offset:43008
	ds_read_b128 v[140:143], v121 offset:57344
	v_mfma_f32_32x32x16_bf16 v[32:47], v[202:205], v[244:247], v[32:47]
	ds_read_b128 v[144:147], v121 offset:59392
	ds_read_b128 v[128:131], v109 offset:34816
	v_mfma_f32_32x32x16_bf16 v[150:165], v[202:205], v[250:253], v[150:165]
	v_mfma_f32_32x32x16_bf16 v[166:181], v[202:205], v[74:77], v[166:181]
	ds_read_b128 v[202:205], v115 offset:32768
	v_mfma_f32_32x32x16_bf16 v[16:31], v[206:209], v[214:217], v[16:31]
	ds_read_b128 v[214:217], v119 offset:40960
	v_mfma_f32_32x32x16_bf16 v[0:15], v[206:209], v[244:247], v[0:15]
	ds_read_b128 v[244:247], v119 offset:43008
	v_mfma_f32_32x32x16_bf16 v[184:199], v[206:209], v[250:253], v[184:199]
	ds_read_b128 v[250:253], v122 offset:57344
	v_mfma_f32_32x32x16_bf16 v[226:241], v[206:209], v[74:77], v[226:241]
	ds_read_b128 v[206:209], v115 offset:34816
	ds_read_b128 v[74:77], v122 offset:59392
	s_waitcnt lgkmcnt(6)
	v_mfma_f32_32x32x16_bf16 v[48:63], v[110:113], v[132:135], v[48:63]
	s_mov_b32 m0, s51
	v_lshl_add_u64 v[64:65], v[64:65], 0, s[44:45]
	global_load_lds_dwordx4 v[64:65], off
	v_mfma_f32_32x32x16_bf16 v[32:47], v[110:113], v[136:139], v[32:47]
	global_load_lds_dwordx4 v[64:65], off offset:1024
	v_mfma_f32_32x32x16_bf16 v[150:165], v[110:113], v[140:143], v[150:165]
	s_mov_b32 m0, s54
	v_lshl_add_u64 v[66:67], v[66:67], 0, s[44:45]
	global_load_lds_dwordx4 v[66:67], off
	v_mfma_f32_32x32x16_bf16 v[166:181], v[110:113], v[144:147], v[166:181]
	global_load_lds_dwordx4 v[66:67], off offset:1024
	v_mfma_f32_32x32x16_bf16 v[16:31], v[128:131], v[132:135], v[16:31]
	s_mov_b32 m0, s57
	v_lshl_add_u64 v[148:149], v[66:67], 0, s[72:73]
	global_load_lds_dwordx4 v[148:149], off
	v_mfma_f32_32x32x16_bf16 v[0:15], v[128:131], v[136:139], v[0:15]
	global_load_lds_dwordx4 v[148:149], off offset:1024
	v_mfma_f32_32x32x16_bf16 v[184:199], v[128:131], v[140:143], v[184:199]
	v_mfma_f32_32x32x16_bf16 v[226:241], v[128:131], v[144:147], v[226:241]
	s_waitcnt vmcnt(6)
	s_waitcnt lgkmcnt(0)
	s_barrier
	ds_read_b128 v[110:113], v109
	ds_read_b128 v[132:135], v114 offset:8192
	v_mfma_f32_32x32x16_bf16 v[48:63], v[202:205], v[214:217], v[48:63]
	ds_read_b128 v[136:139], v114 offset:10240
	ds_read_b128 v[140:143], v114 offset:49152
	v_mfma_f32_32x32x16_bf16 v[32:47], v[202:205], v[244:247], v[32:47]
	ds_read_b128 v[144:147], v114 offset:51200
	ds_read_b128 v[128:131], v109 offset:2048
	v_mfma_f32_32x32x16_bf16 v[150:165], v[202:205], v[250:253], v[150:165]
	v_mfma_f32_32x32x16_bf16 v[166:181], v[202:205], v[74:77], v[166:181]
	ds_read_b128 v[202:205], v115
	v_mfma_f32_32x32x16_bf16 v[16:31], v[206:209], v[214:217], v[16:31]
	ds_read_b128 v[214:217], v119 offset:8192
	v_mfma_f32_32x32x16_bf16 v[0:15], v[206:209], v[244:247], v[0:15]
	ds_read_b128 v[244:247], v119 offset:10240
	v_mfma_f32_32x32x16_bf16 v[184:199], v[206:209], v[250:253], v[184:199]
	ds_read_b128 v[250:253], v119 offset:49152
	v_mfma_f32_32x32x16_bf16 v[226:241], v[206:209], v[74:77], v[226:241]
	ds_read_b128 v[206:209], v115 offset:2048
	ds_read_b128 v[74:77], v119 offset:51200
	s_waitcnt lgkmcnt(6)
	v_mfma_f32_32x32x16_bf16 v[48:63], v[110:113], v[132:135], v[48:63]
	s_mov_b32 m0, s52
	v_lshl_add_u64 v[64:65], v[64:65], 0, s[44:45]
	global_load_lds_dwordx4 v[64:65], off
	v_mfma_f32_32x32x16_bf16 v[32:47], v[110:113], v[136:139], v[32:47]
	global_load_lds_dwordx4 v[64:65], off offset:1024
	v_mfma_f32_32x32x16_bf16 v[150:165], v[110:113], v[140:143], v[150:165]
	s_mov_b32 m0, s55
	v_lshl_add_u64 v[66:67], v[66:67], 0, s[44:45]
	global_load_lds_dwordx4 v[66:67], off
	v_mfma_f32_32x32x16_bf16 v[166:181], v[110:113], v[144:147], v[166:181]
	global_load_lds_dwordx4 v[66:67], off offset:1024
	v_mfma_f32_32x32x16_bf16 v[16:31], v[128:131], v[132:135], v[16:31]
	s_mov_b32 m0, s58
	v_lshl_add_u64 v[148:149], v[66:67], 0, s[72:73]
	global_load_lds_dwordx4 v[148:149], off
	v_mfma_f32_32x32x16_bf16 v[0:15], v[128:131], v[136:139], v[0:15]
	global_load_lds_dwordx4 v[148:149], off offset:1024
	v_mfma_f32_32x32x16_bf16 v[184:199], v[128:131], v[140:143], v[184:199]
	v_mfma_f32_32x32x16_bf16 v[226:241], v[128:131], v[144:147], v[226:241]
	s_waitcnt vmcnt(6)
	s_waitcnt lgkmcnt(0)
	s_barrier
	ds_read_b128 v[110:113], v109 offset:16384
	ds_read_b128 v[132:135], v114 offset:24576
	v_mfma_f32_32x32x16_bf16 v[48:63], v[202:205], v[214:217], v[48:63]
	ds_read_b128 v[136:139], v114 offset:26624
	ds_read_b128 v[140:143], v121 offset:40960
	v_mfma_f32_32x32x16_bf16 v[32:47], v[202:205], v[244:247], v[32:47]
	ds_read_b128 v[144:147], v121 offset:43008
	ds_read_b128 v[128:131], v109 offset:18432
	v_mfma_f32_32x32x16_bf16 v[150:165], v[202:205], v[250:253], v[150:165]
	v_mfma_f32_32x32x16_bf16 v[166:181], v[202:205], v[74:77], v[166:181]
	ds_read_b128 v[202:205], v115 offset:16384
	v_mfma_f32_32x32x16_bf16 v[16:31], v[206:209], v[214:217], v[16:31]
	ds_read_b128 v[214:217], v119 offset:24576
	v_mfma_f32_32x32x16_bf16 v[0:15], v[206:209], v[244:247], v[0:15]
	ds_read_b128 v[244:247], v119 offset:26624
	v_mfma_f32_32x32x16_bf16 v[184:199], v[206:209], v[250:253], v[184:199]
	ds_read_b128 v[250:253], v122 offset:40960
	v_mfma_f32_32x32x16_bf16 v[226:241], v[206:209], v[74:77], v[226:241]
	ds_read_b128 v[206:209], v115 offset:18432
	ds_read_b128 v[74:77], v122 offset:43008
	s_waitcnt lgkmcnt(6)
	v_mfma_f32_32x32x16_bf16 v[48:63], v[110:113], v[132:135], v[48:63]
	s_mov_b32 m0, s50
	v_lshl_add_u64 v[64:65], v[64:65], 0, s[44:45]
	global_load_lds_dwordx4 v[64:65], off
	v_mfma_f32_32x32x16_bf16 v[32:47], v[110:113], v[136:139], v[32:47]
	global_load_lds_dwordx4 v[64:65], off offset:1024
	v_mfma_f32_32x32x16_bf16 v[150:165], v[110:113], v[140:143], v[150:165]
	s_mov_b32 m0, s53
	v_lshl_add_u64 v[66:67], v[66:67], 0, s[44:45]
	global_load_lds_dwordx4 v[66:67], off
	v_mfma_f32_32x32x16_bf16 v[166:181], v[110:113], v[144:147], v[166:181]
	global_load_lds_dwordx4 v[66:67], off offset:1024
	v_mfma_f32_32x32x16_bf16 v[16:31], v[128:131], v[132:135], v[16:31]
	s_mov_b32 m0, s56
	v_lshl_add_u64 v[148:149], v[66:67], 0, s[72:73]
	global_load_lds_dwordx4 v[148:149], off
	v_mfma_f32_32x32x16_bf16 v[0:15], v[128:131], v[136:139], v[0:15]
	global_load_lds_dwordx4 v[148:149], off offset:1024
	v_mfma_f32_32x32x16_bf16 v[184:199], v[128:131], v[140:143], v[184:199]
	v_mfma_f32_32x32x16_bf16 v[226:241], v[128:131], v[144:147], v[226:241]
	s_waitcnt vmcnt(6)
	s_waitcnt lgkmcnt(0)
	s_barrier
	ds_read_b128 v[110:113], v109 offset:32768
	ds_read_b128 v[132:135], v114 offset:40960
	v_mfma_f32_32x32x16_bf16 v[48:63], v[202:205], v[214:217], v[48:63]
	ds_read_b128 v[136:139], v114 offset:43008
	ds_read_b128 v[140:143], v121 offset:57344
	v_mfma_f32_32x32x16_bf16 v[32:47], v[202:205], v[244:247], v[32:47]
	ds_read_b128 v[144:147], v121 offset:59392
	ds_read_b128 v[128:131], v109 offset:34816
	v_mfma_f32_32x32x16_bf16 v[150:165], v[202:205], v[250:253], v[150:165]
	v_mfma_f32_32x32x16_bf16 v[166:181], v[202:205], v[74:77], v[166:181]
	ds_read_b128 v[202:205], v115 offset:32768
	v_mfma_f32_32x32x16_bf16 v[16:31], v[206:209], v[214:217], v[16:31]
	ds_read_b128 v[214:217], v119 offset:40960
	v_mfma_f32_32x32x16_bf16 v[0:15], v[206:209], v[244:247], v[0:15]
	ds_read_b128 v[244:247], v119 offset:43008
	v_mfma_f32_32x32x16_bf16 v[184:199], v[206:209], v[250:253], v[184:199]
	ds_read_b128 v[250:253], v122 offset:57344
	v_mfma_f32_32x32x16_bf16 v[226:241], v[206:209], v[74:77], v[226:241]
	ds_read_b128 v[206:209], v115 offset:34816
	ds_read_b128 v[74:77], v122 offset:59392
	s_waitcnt lgkmcnt(6)
	v_mfma_f32_32x32x16_bf16 v[48:63], v[110:113], v[132:135], v[48:63]
	s_mov_b32 m0, s51
	v_lshl_add_u64 v[64:65], v[64:65], 0, s[44:45]
	global_load_lds_dwordx4 v[64:65], off
	v_mfma_f32_32x32x16_bf16 v[32:47], v[110:113], v[136:139], v[32:47]
	global_load_lds_dwordx4 v[64:65], off offset:1024
	v_mfma_f32_32x32x16_bf16 v[150:165], v[110:113], v[140:143], v[150:165]
	s_mov_b32 m0, s54
	v_lshl_add_u64 v[66:67], v[66:67], 0, s[44:45]
	global_load_lds_dwordx4 v[66:67], off
	v_mfma_f32_32x32x16_bf16 v[166:181], v[110:113], v[144:147], v[166:181]
	global_load_lds_dwordx4 v[66:67], off offset:1024
	v_mfma_f32_32x32x16_bf16 v[16:31], v[128:131], v[132:135], v[16:31]
	s_mov_b32 m0, s57
	v_lshl_add_u64 v[148:149], v[66:67], 0, s[72:73]
	global_load_lds_dwordx4 v[148:149], off
	v_mfma_f32_32x32x16_bf16 v[0:15], v[128:131], v[136:139], v[0:15]
	global_load_lds_dwordx4 v[148:149], off offset:1024
	v_mfma_f32_32x32x16_bf16 v[184:199], v[128:131], v[140:143], v[184:199]
	v_mfma_f32_32x32x16_bf16 v[226:241], v[128:131], v[144:147], v[226:241]
	s_waitcnt vmcnt(6)
	s_waitcnt lgkmcnt(0)
	s_barrier
	ds_read_b128 v[110:113], v109
	ds_read_b128 v[132:135], v114 offset:8192
	v_mfma_f32_32x32x16_bf16 v[48:63], v[202:205], v[214:217], v[48:63]
	ds_read_b128 v[136:139], v114 offset:10240
	ds_read_b128 v[140:143], v114 offset:49152
	v_mfma_f32_32x32x16_bf16 v[32:47], v[202:205], v[244:247], v[32:47]
	ds_read_b128 v[144:147], v114 offset:51200
	ds_read_b128 v[128:131], v109 offset:2048
	v_mfma_f32_32x32x16_bf16 v[150:165], v[202:205], v[250:253], v[150:165]
	v_mfma_f32_32x32x16_bf16 v[166:181], v[202:205], v[74:77], v[166:181]
	ds_read_b128 v[202:205], v115
	v_mfma_f32_32x32x16_bf16 v[16:31], v[206:209], v[214:217], v[16:31]
	ds_read_b128 v[214:217], v119 offset:8192
	v_mfma_f32_32x32x16_bf16 v[0:15], v[206:209], v[244:247], v[0:15]
	ds_read_b128 v[244:247], v119 offset:10240
	v_mfma_f32_32x32x16_bf16 v[184:199], v[206:209], v[250:253], v[184:199]
	ds_read_b128 v[250:253], v119 offset:49152
	v_mfma_f32_32x32x16_bf16 v[226:241], v[206:209], v[74:77], v[226:241]
	ds_read_b128 v[206:209], v115 offset:2048
	ds_read_b128 v[74:77], v119 offset:51200
	s_waitcnt lgkmcnt(6)
	v_mfma_f32_32x32x16_bf16 v[48:63], v[110:113], v[132:135], v[48:63]
	s_mov_b32 m0, s52
	v_lshl_add_u64 v[64:65], v[64:65], 0, s[44:45]
	global_load_lds_dwordx4 v[64:65], off
	v_mfma_f32_32x32x16_bf16 v[32:47], v[110:113], v[136:139], v[32:47]
	global_load_lds_dwordx4 v[64:65], off offset:1024
	v_mfma_f32_32x32x16_bf16 v[150:165], v[110:113], v[140:143], v[150:165]
	s_mov_b32 m0, s55
	v_lshl_add_u64 v[66:67], v[66:67], 0, s[44:45]
	global_load_lds_dwordx4 v[66:67], off
	v_mfma_f32_32x32x16_bf16 v[166:181], v[110:113], v[144:147], v[166:181]
	global_load_lds_dwordx4 v[66:67], off offset:1024
	v_mfma_f32_32x32x16_bf16 v[16:31], v[128:131], v[132:135], v[16:31]
	s_mov_b32 m0, s58
	v_lshl_add_u64 v[148:149], v[66:67], 0, s[72:73]
	global_load_lds_dwordx4 v[148:149], off
	v_mfma_f32_32x32x16_bf16 v[0:15], v[128:131], v[136:139], v[0:15]
	global_load_lds_dwordx4 v[148:149], off offset:1024
	v_mfma_f32_32x32x16_bf16 v[184:199], v[128:131], v[140:143], v[184:199]
	v_mfma_f32_32x32x16_bf16 v[226:241], v[128:131], v[144:147], v[226:241]
	s_waitcnt vmcnt(6)
	s_waitcnt lgkmcnt(0)
	s_barrier
	ds_read_b128 v[110:113], v109 offset:16384
	ds_read_b128 v[132:135], v114 offset:24576
	v_mfma_f32_32x32x16_bf16 v[48:63], v[202:205], v[214:217], v[48:63]
	ds_read_b128 v[136:139], v114 offset:26624
	ds_read_b128 v[140:143], v121 offset:40960
	v_mfma_f32_32x32x16_bf16 v[32:47], v[202:205], v[244:247], v[32:47]
	ds_read_b128 v[144:147], v121 offset:43008
	ds_read_b128 v[128:131], v109 offset:18432
	v_mfma_f32_32x32x16_bf16 v[150:165], v[202:205], v[250:253], v[150:165]
	v_mfma_f32_32x32x16_bf16 v[166:181], v[202:205], v[74:77], v[166:181]
	ds_read_b128 v[202:205], v115 offset:16384
	v_mfma_f32_32x32x16_bf16 v[16:31], v[206:209], v[214:217], v[16:31]
	ds_read_b128 v[214:217], v119 offset:24576
	v_mfma_f32_32x32x16_bf16 v[0:15], v[206:209], v[244:247], v[0:15]
	ds_read_b128 v[244:247], v119 offset:26624
	v_mfma_f32_32x32x16_bf16 v[184:199], v[206:209], v[250:253], v[184:199]
	ds_read_b128 v[250:253], v122 offset:40960
	v_mfma_f32_32x32x16_bf16 v[226:241], v[206:209], v[74:77], v[226:241]
	ds_read_b128 v[206:209], v115 offset:18432
	ds_read_b128 v[74:77], v122 offset:43008
	s_waitcnt lgkmcnt(6)
	v_mfma_f32_32x32x16_bf16 v[48:63], v[110:113], v[132:135], v[48:63]
	s_mov_b32 m0, s50
	v_lshl_add_u64 v[64:65], v[64:65], 0, s[44:45]
	global_load_lds_dwordx4 v[64:65], off
	v_mfma_f32_32x32x16_bf16 v[32:47], v[110:113], v[136:139], v[32:47]
	global_load_lds_dwordx4 v[64:65], off offset:1024
	v_mfma_f32_32x32x16_bf16 v[150:165], v[110:113], v[140:143], v[150:165]
	s_mov_b32 m0, s53
	v_lshl_add_u64 v[66:67], v[66:67], 0, s[44:45]
	global_load_lds_dwordx4 v[66:67], off
	v_mfma_f32_32x32x16_bf16 v[166:181], v[110:113], v[144:147], v[166:181]
	global_load_lds_dwordx4 v[66:67], off offset:1024
	v_mfma_f32_32x32x16_bf16 v[16:31], v[128:131], v[132:135], v[16:31]
	s_mov_b32 m0, s56
	v_lshl_add_u64 v[148:149], v[66:67], 0, s[72:73]
	global_load_lds_dwordx4 v[148:149], off
	v_mfma_f32_32x32x16_bf16 v[0:15], v[128:131], v[136:139], v[0:15]
	global_load_lds_dwordx4 v[148:149], off offset:1024
	v_mfma_f32_32x32x16_bf16 v[184:199], v[128:131], v[140:143], v[184:199]
	v_mfma_f32_32x32x16_bf16 v[226:241], v[128:131], v[144:147], v[226:241]
	s_waitcnt vmcnt(6)
	s_waitcnt lgkmcnt(0)
	s_barrier
	ds_read_b128 v[110:113], v109 offset:32768
	ds_read_b128 v[132:135], v114 offset:40960
	v_mfma_f32_32x32x16_bf16 v[48:63], v[202:205], v[214:217], v[48:63]
	ds_read_b128 v[136:139], v114 offset:43008
	ds_read_b128 v[140:143], v121 offset:57344
	v_mfma_f32_32x32x16_bf16 v[32:47], v[202:205], v[244:247], v[32:47]
	ds_read_b128 v[144:147], v121 offset:59392
	ds_read_b128 v[128:131], v109 offset:34816
	v_mfma_f32_32x32x16_bf16 v[150:165], v[202:205], v[250:253], v[150:165]
	v_mfma_f32_32x32x16_bf16 v[166:181], v[202:205], v[74:77], v[166:181]
	ds_read_b128 v[202:205], v115 offset:32768
	v_mfma_f32_32x32x16_bf16 v[16:31], v[206:209], v[214:217], v[16:31]
	ds_read_b128 v[214:217], v119 offset:40960
	v_mfma_f32_32x32x16_bf16 v[0:15], v[206:209], v[244:247], v[0:15]
	ds_read_b128 v[244:247], v119 offset:43008
	v_mfma_f32_32x32x16_bf16 v[184:199], v[206:209], v[250:253], v[184:199]
	ds_read_b128 v[250:253], v122 offset:57344
	v_mfma_f32_32x32x16_bf16 v[226:241], v[206:209], v[74:77], v[226:241]
	ds_read_b128 v[206:209], v115 offset:34816
	ds_read_b128 v[74:77], v122 offset:59392
	s_waitcnt lgkmcnt(6)
	v_mfma_f32_32x32x16_bf16 v[48:63], v[110:113], v[132:135], v[48:63]
	s_mov_b32 m0, s51
	v_lshl_add_u64 v[64:65], v[64:65], 0, s[44:45]
	global_load_lds_dwordx4 v[64:65], off
	v_mfma_f32_32x32x16_bf16 v[32:47], v[110:113], v[136:139], v[32:47]
	global_load_lds_dwordx4 v[64:65], off offset:1024
	v_mfma_f32_32x32x16_bf16 v[150:165], v[110:113], v[140:143], v[150:165]
	s_mov_b32 m0, s54
	v_lshl_add_u64 v[66:67], v[66:67], 0, s[44:45]
	global_load_lds_dwordx4 v[66:67], off
	v_mfma_f32_32x32x16_bf16 v[166:181], v[110:113], v[144:147], v[166:181]
	global_load_lds_dwordx4 v[66:67], off offset:1024
	v_mfma_f32_32x32x16_bf16 v[16:31], v[128:131], v[132:135], v[16:31]
	s_mov_b32 m0, s57
	v_lshl_add_u64 v[148:149], v[66:67], 0, s[72:73]
	global_load_lds_dwordx4 v[148:149], off
	v_mfma_f32_32x32x16_bf16 v[0:15], v[128:131], v[136:139], v[0:15]
	global_load_lds_dwordx4 v[148:149], off offset:1024
	v_mfma_f32_32x32x16_bf16 v[184:199], v[128:131], v[140:143], v[184:199]
	v_mfma_f32_32x32x16_bf16 v[226:241], v[128:131], v[144:147], v[226:241]
	s_waitcnt vmcnt(6)
	s_waitcnt lgkmcnt(0)
	s_barrier
	ds_read_b128 v[110:113], v109
	ds_read_b128 v[132:135], v114 offset:8192
	v_mfma_f32_32x32x16_bf16 v[48:63], v[202:205], v[214:217], v[48:63]
	ds_read_b128 v[136:139], v114 offset:10240
	ds_read_b128 v[140:143], v114 offset:49152
	v_mfma_f32_32x32x16_bf16 v[32:47], v[202:205], v[244:247], v[32:47]
	ds_read_b128 v[144:147], v114 offset:51200
	ds_read_b128 v[128:131], v109 offset:2048
	v_mfma_f32_32x32x16_bf16 v[150:165], v[202:205], v[250:253], v[150:165]
	v_mfma_f32_32x32x16_bf16 v[166:181], v[202:205], v[74:77], v[166:181]
	ds_read_b128 v[202:205], v115
	v_mfma_f32_32x32x16_bf16 v[16:31], v[206:209], v[214:217], v[16:31]
	ds_read_b128 v[214:217], v119 offset:8192
	v_mfma_f32_32x32x16_bf16 v[0:15], v[206:209], v[244:247], v[0:15]
	ds_read_b128 v[244:247], v119 offset:10240
	v_mfma_f32_32x32x16_bf16 v[184:199], v[206:209], v[250:253], v[184:199]
	ds_read_b128 v[250:253], v119 offset:49152
	v_mfma_f32_32x32x16_bf16 v[226:241], v[206:209], v[74:77], v[226:241]
	ds_read_b128 v[206:209], v115 offset:2048
	ds_read_b128 v[74:77], v119 offset:51200
	s_waitcnt lgkmcnt(6)
	v_mfma_f32_32x32x16_bf16 v[48:63], v[110:113], v[132:135], v[48:63]
	v_mfma_f32_32x32x16_bf16 v[32:47], v[110:113], v[136:139], v[32:47]
	v_mfma_f32_32x32x16_bf16 v[150:165], v[110:113], v[140:143], v[150:165]
	v_mfma_f32_32x32x16_bf16 v[166:181], v[110:113], v[144:147], v[166:181]
	v_mfma_f32_32x32x16_bf16 v[16:31], v[128:131], v[132:135], v[16:31]
	v_mfma_f32_32x32x16_bf16 v[0:15], v[128:131], v[136:139], v[0:15]
	v_mfma_f32_32x32x16_bf16 v[184:199], v[128:131], v[140:143], v[184:199]
	v_mfma_f32_32x32x16_bf16 v[226:241], v[128:131], v[144:147], v[226:241]
	s_waitcnt vmcnt(0)
	s_waitcnt lgkmcnt(0)
	s_barrier
	ds_read_b128 v[110:113], v109 offset:16384
	ds_read_b128 v[132:135], v114 offset:24576
	v_mfma_f32_32x32x16_bf16 v[48:63], v[202:205], v[214:217], v[48:63]
	ds_read_b128 v[136:139], v114 offset:26624
	ds_read_b128 v[140:143], v121 offset:40960
	v_mfma_f32_32x32x16_bf16 v[32:47], v[202:205], v[244:247], v[32:47]
	ds_read_b128 v[144:147], v121 offset:43008
	ds_read_b128 v[128:131], v109 offset:18432
	v_mfma_f32_32x32x16_bf16 v[150:165], v[202:205], v[250:253], v[150:165]
	v_mfma_f32_32x32x16_bf16 v[166:181], v[202:205], v[74:77], v[166:181]
	ds_read_b128 v[202:205], v115 offset:16384
	v_mfma_f32_32x32x16_bf16 v[16:31], v[206:209], v[214:217], v[16:31]
	ds_read_b128 v[214:217], v119 offset:24576
	v_mfma_f32_32x32x16_bf16 v[0:15], v[206:209], v[244:247], v[0:15]
	ds_read_b128 v[244:247], v119 offset:26624
	v_mfma_f32_32x32x16_bf16 v[184:199], v[206:209], v[250:253], v[184:199]
	ds_read_b128 v[250:253], v122 offset:40960
	v_mfma_f32_32x32x16_bf16 v[226:241], v[206:209], v[74:77], v[226:241]
	ds_read_b128 v[206:209], v115 offset:18432
	ds_read_b128 v[74:77], v122 offset:43008
	s_waitcnt lgkmcnt(6)
	v_mfma_f32_32x32x16_bf16 v[48:63], v[110:113], v[132:135], v[48:63]
	v_mfma_f32_32x32x16_bf16 v[32:47], v[110:113], v[136:139], v[32:47]
	v_mfma_f32_32x32x16_bf16 v[150:165], v[110:113], v[140:143], v[150:165]
	v_mfma_f32_32x32x16_bf16 v[166:181], v[110:113], v[144:147], v[166:181]
	v_mfma_f32_32x32x16_bf16 v[16:31], v[128:131], v[132:135], v[16:31]
	v_mfma_f32_32x32x16_bf16 v[0:15], v[128:131], v[136:139], v[0:15]
	v_mfma_f32_32x32x16_bf16 v[184:199], v[128:131], v[140:143], v[184:199]
	v_mfma_f32_32x32x16_bf16 v[226:241], v[128:131], v[144:147], v[226:241]
	s_waitcnt lgkmcnt(0)
	v_mfma_f32_32x32x16_bf16 v[48:63], v[202:205], v[214:217], v[48:63]
	v_mfma_f32_32x32x16_bf16 v[32:47], v[202:205], v[244:247], v[32:47]
	v_mfma_f32_32x32x16_bf16 v[150:165], v[202:205], v[250:253], v[150:165]
	v_mfma_f32_32x32x16_bf16 v[166:181], v[202:205], v[74:77], v[166:181]
	v_mfma_f32_32x32x16_bf16 v[16:31], v[206:209], v[214:217], v[16:31]
	v_mfma_f32_32x32x16_bf16 v[0:15], v[206:209], v[244:247], v[0:15]
	v_mfma_f32_32x32x16_bf16 v[184:199], v[206:209], v[250:253], v[184:199]
	v_mfma_f32_32x32x16_bf16 v[226:241], v[206:209], v[74:77], v[226:241]
	v_add_u32_e32 v77, 0x4400, v88
	v_add_u32_e32 v76, 0x6000, v88
	v_add_u32_e32 v75, 0x6400, v88
	v_add_u32_e32 v74, 0x8000, v88
	s_branch .Lgu_post
